# GEMM mainloops: per-segment s_setprio flips removed, one static s_setprio 1 for waves 4-7 over each GEMM phase
# speedup vs baseline: 1.0029x; 1.0007x over previous
.LBB0_128:
	s_or_b64 exec, exec, s[0:1]
	v_readfirstlane_b32 s98, v210
	s_nop 3
	s_lshr_b32 s98, s98, 6
	s_cmp_ge_u32 s98, 4
	s_cbranch_scc0 .Lgprio_skip0
	s_setprio 1
.Lgprio_skip0:
	s_bitcmp1_b32 s2, 0
	s_cbranch_scc0 .Ldf_skip_p1
	v_writelane_b32 v234, s0, 0
	v_writelane_b32 v234, s1, 1
	v_writelane_b32 v234, s2, 2
	v_writelane_b32 v234, s3, 3
	v_writelane_b32 v234, s4, 4
	v_writelane_b32 v234, s5, 5
	v_writelane_b32 v234, s6, 6
	v_writelane_b32 v234, s7, 7
	v_writelane_b32 v234, s8, 8
	v_writelane_b32 v234, s9, 9
	v_writelane_b32 v234, s10, 10
	v_writelane_b32 v234, s11, 11
	v_writelane_b32 v234, s12, 12
	v_writelane_b32 v234, s13, 13
	v_writelane_b32 v234, s14, 14
	v_writelane_b32 v234, s15, 15
	v_writelane_b32 v234, s16, 16
	v_writelane_b32 v234, s17, 17
	v_writelane_b32 v234, s18, 18
	v_writelane_b32 v234, s19, 19
	v_writelane_b32 v234, s20, 20
	v_writelane_b32 v234, s21, 21
	v_writelane_b32 v234, s22, 22
	v_writelane_b32 v234, s23, 23
	v_writelane_b32 v234, s24, 24
	v_writelane_b32 v234, s25, 25
	v_writelane_b32 v234, s26, 26
	v_writelane_b32 v234, s27, 27
	v_writelane_b32 v234, s28, 28
	v_writelane_b32 v234, s29, 29
	v_writelane_b32 v234, s30, 30
	v_writelane_b32 v234, s31, 31
	v_writelane_b32 v234, s32, 32
	v_writelane_b32 v234, s33, 33
	v_writelane_b32 v234, s34, 34
	v_writelane_b32 v234, s35, 35
	v_writelane_b32 v234, s36, 36
	v_writelane_b32 v234, s37, 37
	v_writelane_b32 v234, s38, 38
	v_writelane_b32 v234, s39, 39
	v_writelane_b32 v234, s40, 40
	v_writelane_b32 v234, s41, 41
	v_writelane_b32 v234, s42, 42
	v_writelane_b32 v234, s43, 43
	v_writelane_b32 v234, s44, 44
	v_writelane_b32 v234, s45, 45
	v_writelane_b32 v234, s46, 46
	v_writelane_b32 v234, s47, 47
	v_writelane_b32 v234, s48, 48
	v_writelane_b32 v234, s49, 49
	v_writelane_b32 v234, s50, 50
	v_writelane_b32 v234, s51, 51
	v_writelane_b32 v234, s52, 52
	v_writelane_b32 v234, s53, 53
	v_writelane_b32 v234, s54, 54
	v_writelane_b32 v234, s55, 55
	v_writelane_b32 v234, s56, 56
	v_writelane_b32 v234, s57, 57
	v_writelane_b32 v234, s58, 58
	v_writelane_b32 v234, s59, 59
	v_writelane_b32 v234, s60, 60
	v_writelane_b32 v234, s61, 61
	v_writelane_b32 v234, s62, 62
	v_writelane_b32 v234, s63, 63
	v_writelane_b32 v235, s64, 0
	v_writelane_b32 v235, s65, 1
	v_writelane_b32 v235, s66, 2
	v_writelane_b32 v235, s67, 3
	v_writelane_b32 v235, s68, 4
	v_writelane_b32 v235, s69, 5
	v_writelane_b32 v235, s70, 6
	v_writelane_b32 v235, s71, 7
	v_writelane_b32 v235, s72, 8
	v_writelane_b32 v235, s73, 9
	v_writelane_b32 v235, s74, 10
	v_writelane_b32 v235, s75, 11
	v_writelane_b32 v235, s76, 12
	v_writelane_b32 v235, s77, 13
	v_writelane_b32 v235, s78, 14
	v_writelane_b32 v235, s79, 15
	v_writelane_b32 v235, s80, 16
	v_writelane_b32 v235, s81, 17
	v_writelane_b32 v235, s82, 18
	v_writelane_b32 v235, s83, 19
	v_writelane_b32 v235, s84, 20
	v_writelane_b32 v235, s85, 21
	v_writelane_b32 v235, s86, 22
	v_writelane_b32 v235, s87, 23
	v_writelane_b32 v235, s88, 24
	v_writelane_b32 v235, s89, 25
	v_writelane_b32 v235, s90, 26
	v_writelane_b32 v235, s91, 27
	v_writelane_b32 v235, s92, 28
	v_writelane_b32 v235, s93, 29
	v_writelane_b32 v235, s94, 30
	v_writelane_b32 v235, s95, 31
	v_writelane_b32 v235, s96, 32
	v_writelane_b32 v235, s97, 33
	v_writelane_b32 v235, vcc_lo, 34
	v_writelane_b32 v235, vcc_hi, 35
	v_readlane_b32 s72, v233, 47
	v_readlane_b32 s73, v233, 48
	v_readlane_b32 s74, v233, 49
	v_readlane_b32 s75, v233, 50
	v_readlane_b32 s76, v233, 51
	v_readlane_b32 s77, v233, 52
	s_add_u32 s62, s92, 0x400000
	s_addc_u32 s63, s93, 0
	v_mov_b32_e32 v1, v210
	s_nop 0
	v_readfirstlane_b32 s0, v1
	v_and_b32_e32 v76, 63, v1
	s_nop 3
	s_ashr_i32 s8, s0, 6
	s_lshr_b32 s1, s2, 1
	s_lshl_b32 s1, s1, 0
	s_and_b32 s3, s2, 0
	s_or_b32 s1, s1, s3
	s_lshl_b32 s1, s1, 3
	s_add_i32 s26, s8, s1
	s_addk_i32 s26, 0x1000
	s_movk_i32 s96, 0x400
	s_movk_i32 s101, 0x1c7f
	s_mov_b32 s100, 1
	s_branch .Lp0_setup

.LBB0_143:
	ds_read_b128 v[148:151], v173
	ds_read_b128 v[152:155], v173 offset:1024
	ds_read_b128 v[156:159], v173 offset:2048
	ds_read_b128 v[160:163], v173 offset:3072
	ds_read_b128 v[164:167], v174
	ds_read_b128 v[168:171], v174 offset:1024
	ds_read_b128 v[176:179], v174 offset:2048
	ds_read_b128 v[180:183], v174 offset:3072
	s_add_u32 s20, s18, 0xfff80080
	s_addc_u32 s21, s19, -1
	s_cmp_eq_u32 s69, 28
	s_cselect_b32 s23, s13, s21
	s_cselect_b32 s22, s15, s20
	s_cselect_b32 s21, s40, s43
	s_cselect_b32 s20, s41, s42
	v_lshl_add_u64 v[208:209], s[18:19], 0, v[140:141]
	s_add_i32 m0, s80, 0xc000
	ds_read_b128 v[184:187], v175
	ds_read_b128 v[188:191], v175 offset:1024
	ds_read_b128 v[192:195], v175 offset:2048
	ds_read_b128 v[196:199], v175 offset:3072
	ds_read_b128 v[200:203], v175 offset:4096
	ds_read_b128 v[204:207], v175 offset:5120
	ds_read_b128 v[212:215], v175 offset:6144
	ds_read_b128 v[216:219], v175 offset:7168
	global_load_lds_dwordx4 v[208:209], off
	v_lshl_add_u64 v[208:209], s[18:19], 0, v[142:143]
	s_add_i32 m0, s80, 0xe000
	s_nop 0
	global_load_lds_dwordx4 v[208:209], off
	s_waitcnt vmcnt(8)
	s_waitcnt lgkmcnt(0)
	s_barrier
	s_waitcnt lgkmcnt(0)
	v_mfma_f32_16x16x32_bf16 v[124:127], v[148:151], v[184:187], v[124:127]
	v_mfma_f32_16x16x32_bf16 v[120:123], v[156:159], v[184:187], v[120:123]
	v_mfma_f32_16x16x32_bf16 v[116:119], v[148:151], v[192:195], v[116:119]
	v_mfma_f32_16x16x32_bf16 v[112:115], v[156:159], v[192:195], v[112:115]
	v_mfma_f32_16x16x32_bf16 v[108:111], v[148:151], v[200:203], v[108:111]
	v_mfma_f32_16x16x32_bf16 v[104:107], v[156:159], v[200:203], v[104:107]
	v_mfma_f32_16x16x32_bf16 v[100:103], v[148:151], v[212:215], v[100:103]
	v_mfma_f32_16x16x32_bf16 v[96:99], v[156:159], v[212:215], v[96:99]
	v_mfma_f32_16x16x32_bf16 v[124:127], v[152:155], v[188:191], v[124:127]
	v_mfma_f32_16x16x32_bf16 v[120:123], v[160:163], v[188:191], v[120:123]
	v_mfma_f32_16x16x32_bf16 v[116:119], v[152:155], v[196:199], v[116:119]
	v_mfma_f32_16x16x32_bf16 v[112:115], v[160:163], v[196:199], v[112:115]
	v_mfma_f32_16x16x32_bf16 v[108:111], v[152:155], v[204:207], v[108:111]
	v_mfma_f32_16x16x32_bf16 v[104:107], v[160:163], v[204:207], v[104:107]
	v_mfma_f32_16x16x32_bf16 v[100:103], v[152:155], v[216:219], v[100:103]
	v_mfma_f32_16x16x32_bf16 v[96:99], v[160:163], v[216:219], v[96:99]
	v_mfma_f32_16x16x32_bf16 v[60:63], v[164:167], v[184:187], v[60:63]
	v_mfma_f32_16x16x32_bf16 v[56:59], v[176:179], v[184:187], v[56:59]
	v_mfma_f32_16x16x32_bf16 v[52:55], v[164:167], v[192:195], v[52:55]
	v_mfma_f32_16x16x32_bf16 v[48:51], v[176:179], v[192:195], v[48:51]
	v_mfma_f32_16x16x32_bf16 v[44:47], v[164:167], v[200:203], v[44:47]
	v_mfma_f32_16x16x32_bf16 v[40:43], v[176:179], v[200:203], v[40:43]
	v_mfma_f32_16x16x32_bf16 v[36:39], v[164:167], v[212:215], v[36:39]
	v_mfma_f32_16x16x32_bf16 v[32:35], v[176:179], v[212:215], v[32:35]
	v_mfma_f32_16x16x32_bf16 v[60:63], v[168:171], v[188:191], v[60:63]
	v_mfma_f32_16x16x32_bf16 v[56:59], v[180:183], v[188:191], v[56:59]
	v_mfma_f32_16x16x32_bf16 v[52:55], v[168:171], v[196:199], v[52:55]
	v_mfma_f32_16x16x32_bf16 v[48:51], v[180:183], v[196:199], v[48:51]
	v_mfma_f32_16x16x32_bf16 v[44:47], v[168:171], v[204:207], v[44:47]
	v_mfma_f32_16x16x32_bf16 v[40:43], v[180:183], v[204:207], v[40:43]
	v_mfma_f32_16x16x32_bf16 v[36:39], v[168:171], v[216:219], v[36:39]
	v_mfma_f32_16x16x32_bf16 v[32:35], v[180:183], v[216:219], v[32:35]
	s_barrier
	s_add_i32 s24, s91, s33
	v_lshl_add_u64 v[208:209], s[20:21], 0, v[130:131]
	s_mov_b32 m0, s24
	ds_read_b128 v[184:187], v175 offset:16384
	ds_read_b128 v[188:191], v175 offset:17408
	ds_read_b128 v[192:195], v175 offset:18432
	ds_read_b128 v[196:199], v175 offset:19456
	ds_read_b128 v[200:203], v175 offset:20480
	ds_read_b128 v[204:207], v175 offset:21504
	ds_read_b128 v[212:215], v175 offset:22528
	ds_read_b128 v[216:219], v175 offset:23552
	global_load_lds_dwordx4 v[208:209], off
	s_add_i32 m0, s24, 0x2000
	s_add_u32 s24, s20, 0x80000
	v_lshl_add_u64 v[220:221], s[20:21], 0, v[134:135]
	s_addc_u32 s25, s21, 0
	s_add_i32 s26, s97, s33
	global_load_lds_dwordx4 v[220:221], off
	v_lshl_add_u64 v[222:223], s[24:25], 0, v[130:131]
	s_mov_b32 m0, s26
	v_lshl_add_u64 v[224:225], s[22:23], 0, v[132:133]
	global_load_lds_dwordx4 v[222:223], off
	v_lshl_add_u64 v[222:223], s[24:25], 0, v[134:135]
	s_add_i32 m0, s26, 0x2000
	s_nop 0
	global_load_lds_dwordx4 v[222:223], off
	v_lshl_add_u64 v[222:223], s[22:23], 0, v[128:129]
	s_mov_b32 m0, s80
	s_nop 0
	global_load_lds_dwordx4 v[222:223], off
	s_mov_b32 m0, s81
	s_nop 0
	global_load_lds_dwordx4 v[224:225], off
	s_waitcnt vmcnt(8)
	s_waitcnt lgkmcnt(0)
	s_barrier
	s_waitcnt lgkmcnt(0)
	v_mfma_f32_16x16x32_bf16 v[92:95], v[148:151], v[184:187], v[92:95]
	v_mfma_f32_16x16x32_bf16 v[88:91], v[156:159], v[184:187], v[88:91]
	v_mfma_f32_16x16x32_bf16 v[84:87], v[148:151], v[192:195], v[84:87]
	v_mfma_f32_16x16x32_bf16 v[80:83], v[156:159], v[192:195], v[80:83]
	v_mfma_f32_16x16x32_bf16 v[76:79], v[148:151], v[200:203], v[76:79]
	v_mfma_f32_16x16x32_bf16 v[72:75], v[156:159], v[200:203], v[72:75]
	v_mfma_f32_16x16x32_bf16 v[68:71], v[148:151], v[212:215], v[68:71]
	v_mfma_f32_16x16x32_bf16 v[64:67], v[156:159], v[212:215], v[64:67]
	v_mfma_f32_16x16x32_bf16 v[92:95], v[152:155], v[188:191], v[92:95]
	v_mfma_f32_16x16x32_bf16 v[88:91], v[160:163], v[188:191], v[88:91]
	v_mfma_f32_16x16x32_bf16 v[84:87], v[152:155], v[196:199], v[84:87]
	v_mfma_f32_16x16x32_bf16 v[80:83], v[160:163], v[196:199], v[80:83]
	v_mfma_f32_16x16x32_bf16 v[76:79], v[152:155], v[204:207], v[76:79]
	v_mfma_f32_16x16x32_bf16 v[72:75], v[160:163], v[204:207], v[72:75]
	v_mfma_f32_16x16x32_bf16 v[68:71], v[152:155], v[216:219], v[68:71]
	v_mfma_f32_16x16x32_bf16 v[64:67], v[160:163], v[216:219], v[64:67]
	v_mfma_f32_16x16x32_bf16 v[28:31], v[164:167], v[184:187], v[28:31]
	v_mfma_f32_16x16x32_bf16 v[24:27], v[176:179], v[184:187], v[24:27]
	v_mfma_f32_16x16x32_bf16 v[20:23], v[164:167], v[192:195], v[20:23]
	v_mfma_f32_16x16x32_bf16 v[16:19], v[176:179], v[192:195], v[16:19]
	v_mfma_f32_16x16x32_bf16 v[12:15], v[164:167], v[200:203], v[12:15]
	v_mfma_f32_16x16x32_bf16 v[8:11], v[176:179], v[200:203], v[8:11]
	v_mfma_f32_16x16x32_bf16 v[4:7], v[164:167], v[212:215], v[4:7]
	v_mfma_f32_16x16x32_bf16 v[0:3], v[176:179], v[212:215], v[0:3]
	v_mfma_f32_16x16x32_bf16 v[28:31], v[168:171], v[188:191], v[28:31]
	v_mfma_f32_16x16x32_bf16 v[24:27], v[180:183], v[188:191], v[24:27]
	v_mfma_f32_16x16x32_bf16 v[20:23], v[168:171], v[196:199], v[20:23]
	v_mfma_f32_16x16x32_bf16 v[16:19], v[180:183], v[196:199], v[16:19]
	v_mfma_f32_16x16x32_bf16 v[12:15], v[168:171], v[204:207], v[12:15]
	v_mfma_f32_16x16x32_bf16 v[8:11], v[180:183], v[204:207], v[8:11]
	v_mfma_f32_16x16x32_bf16 v[4:7], v[168:171], v[216:219], v[4:7]
	v_mfma_f32_16x16x32_bf16 v[0:3], v[180:183], v[216:219], v[0:3]
	s_barrier
	s_add_i32 s24, 0, 0x18000
	v_add_u32_e32 v136, s24, v172
	s_add_i32 s25, 0, 0x1c000
	ds_read_b128 v[148:151], v136
	ds_read_b128 v[152:155], v136 offset:1024
	ds_read_b128 v[156:159], v136 offset:2048
	ds_read_b128 v[160:163], v136 offset:3072
	v_add_u32_e32 v136, s25, v172
	ds_read_b128 v[164:167], v136
	ds_read_b128 v[168:171], v136 offset:1024
	ds_read_b128 v[176:179], v136 offset:2048
	ds_read_b128 v[180:183], v136 offset:3072
	s_add_u32 s22, s22, 0x80000
	s_addc_u32 s23, s23, 0
	s_mov_b32 m0, s82
	v_lshl_add_u64 v[226:227], s[22:23], 0, v[128:129]
	ds_read_b128 v[184:187], v175 offset:32768
	ds_read_b128 v[188:191], v175 offset:33792
	ds_read_b128 v[192:195], v175 offset:34816
	ds_read_b128 v[196:199], v175 offset:35840
	ds_read_b128 v[200:203], v175 offset:36864
	ds_read_b128 v[204:207], v175 offset:37888
	ds_read_b128 v[212:215], v175 offset:38912
	ds_read_b128 v[216:219], v175 offset:39936
	global_load_lds_dwordx4 v[226:227], off
	v_lshl_add_u64 v[226:227], s[22:23], 0, v[132:133]
	s_mov_b32 m0, s83
	s_nop 0
	global_load_lds_dwordx4 v[226:227], off
	s_waitcnt vmcnt(8)
	s_waitcnt lgkmcnt(0)
	s_barrier
	s_waitcnt lgkmcnt(0)
	v_mfma_f32_16x16x32_bf16 v[124:127], v[148:151], v[184:187], v[124:127]
	v_mfma_f32_16x16x32_bf16 v[120:123], v[156:159], v[184:187], v[120:123]
	v_mfma_f32_16x16x32_bf16 v[116:119], v[148:151], v[192:195], v[116:119]
	v_mfma_f32_16x16x32_bf16 v[112:115], v[156:159], v[192:195], v[112:115]
	v_mfma_f32_16x16x32_bf16 v[108:111], v[148:151], v[200:203], v[108:111]
	v_mfma_f32_16x16x32_bf16 v[104:107], v[156:159], v[200:203], v[104:107]
	v_mfma_f32_16x16x32_bf16 v[100:103], v[148:151], v[212:215], v[100:103]
	v_mfma_f32_16x16x32_bf16 v[96:99], v[156:159], v[212:215], v[96:99]
	v_mfma_f32_16x16x32_bf16 v[124:127], v[152:155], v[188:191], v[124:127]
	v_mfma_f32_16x16x32_bf16 v[120:123], v[160:163], v[188:191], v[120:123]
	v_mfma_f32_16x16x32_bf16 v[116:119], v[152:155], v[196:199], v[116:119]
	v_mfma_f32_16x16x32_bf16 v[112:115], v[160:163], v[196:199], v[112:115]
	v_mfma_f32_16x16x32_bf16 v[108:111], v[152:155], v[204:207], v[108:111]
	v_mfma_f32_16x16x32_bf16 v[104:107], v[160:163], v[204:207], v[104:107]
	v_mfma_f32_16x16x32_bf16 v[100:103], v[152:155], v[216:219], v[100:103]
	v_mfma_f32_16x16x32_bf16 v[96:99], v[160:163], v[216:219], v[96:99]
	v_mfma_f32_16x16x32_bf16 v[60:63], v[164:167], v[184:187], v[60:63]
	v_mfma_f32_16x16x32_bf16 v[56:59], v[176:179], v[184:187], v[56:59]
	v_mfma_f32_16x16x32_bf16 v[52:55], v[164:167], v[192:195], v[52:55]
	v_mfma_f32_16x16x32_bf16 v[48:51], v[176:179], v[192:195], v[48:51]
	v_mfma_f32_16x16x32_bf16 v[44:47], v[164:167], v[200:203], v[44:47]
	v_mfma_f32_16x16x32_bf16 v[40:43], v[176:179], v[200:203], v[40:43]
	v_mfma_f32_16x16x32_bf16 v[36:39], v[164:167], v[212:215], v[36:39]
	v_mfma_f32_16x16x32_bf16 v[32:35], v[176:179], v[212:215], v[32:35]
	v_mfma_f32_16x16x32_bf16 v[60:63], v[168:171], v[188:191], v[60:63]
	v_mfma_f32_16x16x32_bf16 v[56:59], v[180:183], v[188:191], v[56:59]
	v_mfma_f32_16x16x32_bf16 v[52:55], v[168:171], v[196:199], v[52:55]
	v_mfma_f32_16x16x32_bf16 v[48:51], v[180:183], v[196:199], v[48:51]
	v_mfma_f32_16x16x32_bf16 v[44:47], v[168:171], v[204:207], v[44:47]
	v_mfma_f32_16x16x32_bf16 v[40:43], v[180:183], v[204:207], v[40:43]
	v_mfma_f32_16x16x32_bf16 v[36:39], v[168:171], v[216:219], v[36:39]
	v_mfma_f32_16x16x32_bf16 v[32:35], v[180:183], v[216:219], v[32:35]
	s_barrier
	s_add_i32 s22, s24, s33
	v_lshl_add_u64 v[208:209], v[208:209], 0, s[64:65]
	s_mov_b32 m0, s22
	ds_read_b128 v[184:187], v175 offset:49152
	ds_read_b128 v[188:191], v175 offset:50176
	ds_read_b128 v[192:195], v175 offset:51200
	ds_read_b128 v[196:199], v175 offset:52224
	ds_read_b128 v[200:203], v175 offset:53248
	ds_read_b128 v[204:207], v175 offset:54272
	ds_read_b128 v[212:215], v175 offset:55296
	ds_read_b128 v[216:219], v175 offset:56320
	global_load_lds_dwordx4 v[208:209], off
	s_add_i32 m0, s22, 0x2000
	s_add_u32 s20, s20, 0x80080
	v_lshl_add_u64 v[208:209], v[220:221], 0, s[64:65]
	s_addc_u32 s21, s21, 0
	s_add_i32 s22, s25, s33
	global_load_lds_dwordx4 v[208:209], off
	v_lshl_add_u64 v[208:209], s[20:21], 0, v[130:131]
	s_mov_b32 m0, s22
	s_nop 0
	global_load_lds_dwordx4 v[208:209], off
	v_lshl_add_u64 v[208:209], s[20:21], 0, v[134:135]
	s_add_i32 m0, s22, 0x2000
	s_nop 0
	global_load_lds_dwordx4 v[208:209], off
	v_lshl_add_u64 v[208:209], v[222:223], 0, s[64:65]
	s_mov_b32 m0, s89
	s_nop 0
	global_load_lds_dwordx4 v[208:209], off
	v_lshl_add_u64 v[208:209], v[224:225], 0, s[64:65]
	s_mov_b32 m0, s90
	s_nop 0
	global_load_lds_dwordx4 v[208:209], off
	s_waitcnt vmcnt(8)
	s_waitcnt lgkmcnt(0)
	s_barrier
	s_waitcnt lgkmcnt(0)
	v_mfma_f32_16x16x32_bf16 v[92:95], v[148:151], v[184:187], v[92:95]
	v_mfma_f32_16x16x32_bf16 v[88:91], v[156:159], v[184:187], v[88:91]
	v_mfma_f32_16x16x32_bf16 v[84:87], v[148:151], v[192:195], v[84:87]
	v_mfma_f32_16x16x32_bf16 v[80:83], v[156:159], v[192:195], v[80:83]
	v_mfma_f32_16x16x32_bf16 v[76:79], v[148:151], v[200:203], v[76:79]
	v_mfma_f32_16x16x32_bf16 v[72:75], v[156:159], v[200:203], v[72:75]
	v_mfma_f32_16x16x32_bf16 v[68:71], v[148:151], v[212:215], v[68:71]
	v_mfma_f32_16x16x32_bf16 v[64:67], v[156:159], v[212:215], v[64:67]
	v_mfma_f32_16x16x32_bf16 v[92:95], v[152:155], v[188:191], v[92:95]
	v_mfma_f32_16x16x32_bf16 v[88:91], v[160:163], v[188:191], v[88:91]
	v_mfma_f32_16x16x32_bf16 v[84:87], v[152:155], v[196:199], v[84:87]
	v_mfma_f32_16x16x32_bf16 v[80:83], v[160:163], v[196:199], v[80:83]
	v_mfma_f32_16x16x32_bf16 v[76:79], v[152:155], v[204:207], v[76:79]
	v_mfma_f32_16x16x32_bf16 v[72:75], v[160:163], v[204:207], v[72:75]
	v_mfma_f32_16x16x32_bf16 v[68:71], v[152:155], v[216:219], v[68:71]
	v_mfma_f32_16x16x32_bf16 v[64:67], v[160:163], v[216:219], v[64:67]
	v_mfma_f32_16x16x32_bf16 v[28:31], v[164:167], v[184:187], v[28:31]
	v_mfma_f32_16x16x32_bf16 v[24:27], v[176:179], v[184:187], v[24:27]
	v_mfma_f32_16x16x32_bf16 v[20:23], v[164:167], v[192:195], v[20:23]
	v_mfma_f32_16x16x32_bf16 v[16:19], v[176:179], v[192:195], v[16:19]
	v_mfma_f32_16x16x32_bf16 v[12:15], v[164:167], v[200:203], v[12:15]
	v_mfma_f32_16x16x32_bf16 v[8:11], v[176:179], v[200:203], v[8:11]
	v_mfma_f32_16x16x32_bf16 v[4:7], v[164:167], v[212:215], v[4:7]
	v_mfma_f32_16x16x32_bf16 v[0:3], v[176:179], v[212:215], v[0:3]
	v_mfma_f32_16x16x32_bf16 v[28:31], v[168:171], v[188:191], v[28:31]
	v_mfma_f32_16x16x32_bf16 v[24:27], v[180:183], v[188:191], v[24:27]
	v_mfma_f32_16x16x32_bf16 v[20:23], v[168:171], v[196:199], v[20:23]
	v_mfma_f32_16x16x32_bf16 v[16:19], v[180:183], v[196:199], v[16:19]
	v_mfma_f32_16x16x32_bf16 v[12:15], v[168:171], v[204:207], v[12:15]
	v_mfma_f32_16x16x32_bf16 v[8:11], v[180:183], v[204:207], v[8:11]
	v_mfma_f32_16x16x32_bf16 v[4:7], v[168:171], v[216:219], v[4:7]
	v_mfma_f32_16x16x32_bf16 v[0:3], v[180:183], v[216:219], v[0:3]
	s_barrier
	s_add_i32 s69, s69, 2
	s_add_u32 s18, s18, 0x100
	s_addc_u32 s19, s19, 0
	s_add_u32 s42, s42, 0x100
	s_addc_u32 s43, s43, 0
	s_cmp_gt_u32 s69, 29
	s_cbranch_scc0 .LBB0_143
	s_and_b64 vcc, exec, s[66:67]
	s_cbranch_vccz .LBB0_146
	s_barrier

.LBB0_308:
	s_or_b64 exec, exec, s[0:1]
	s_setprio 0
	s_waitcnt lgkmcnt(0)
	v_mov_b32_e32 v0, v210
	s_barrier
	s_nop 0
	v_readfirstlane_b32 s0, v0
	s_ashr_i32 s12, s0, 6
	s_cmp_lt_i32 s12, 4
	s_cbranch_scc1 .LBB0_310
	s_cmp_lg_u32 s12, 4
	s_cselect_b64 s[0:1], -1, 0
	s_cbranch_execz .LBB0_311
	s_branch .LBB0_312

.Lgprio_skip1:
	s_bitcmp1_b32 s2, 0
	s_cbranch_scc0 .Ldf_skip_p3
	v_writelane_b32 v234, s0, 0
	v_writelane_b32 v234, s1, 1
	v_writelane_b32 v234, s2, 2
	v_writelane_b32 v234, s3, 3
	v_writelane_b32 v234, s4, 4
	v_writelane_b32 v234, s5, 5
	v_writelane_b32 v234, s6, 6
	v_writelane_b32 v234, s7, 7
	v_writelane_b32 v234, s8, 8
	v_writelane_b32 v234, s9, 9
	v_writelane_b32 v234, s10, 10
	v_writelane_b32 v234, s11, 11
	v_writelane_b32 v234, s12, 12
	v_writelane_b32 v234, s13, 13
	v_writelane_b32 v234, s14, 14
	v_writelane_b32 v234, s15, 15
	v_writelane_b32 v234, s16, 16
	v_writelane_b32 v234, s17, 17
	v_writelane_b32 v234, s18, 18
	v_writelane_b32 v234, s19, 19
	v_writelane_b32 v234, s20, 20
	v_writelane_b32 v234, s21, 21
	v_writelane_b32 v234, s22, 22
	v_writelane_b32 v234, s23, 23
	v_writelane_b32 v234, s24, 24
	v_writelane_b32 v234, s25, 25
	v_writelane_b32 v234, s26, 26
	v_writelane_b32 v234, s27, 27
	v_writelane_b32 v234, s28, 28
	v_writelane_b32 v234, s29, 29
	v_writelane_b32 v234, s30, 30
	v_writelane_b32 v234, s31, 31
	v_writelane_b32 v234, s32, 32
	v_writelane_b32 v234, s33, 33
	v_writelane_b32 v234, s34, 34
	v_writelane_b32 v234, s35, 35
	v_writelane_b32 v234, s36, 36
	v_writelane_b32 v234, s37, 37
	v_writelane_b32 v234, s38, 38
	v_writelane_b32 v234, s39, 39
	v_writelane_b32 v234, s40, 40
	v_writelane_b32 v234, s41, 41
	v_writelane_b32 v234, s42, 42
	v_writelane_b32 v234, s43, 43
	v_writelane_b32 v234, s44, 44
	v_writelane_b32 v234, s45, 45
	v_writelane_b32 v234, s46, 46
	v_writelane_b32 v234, s47, 47
	v_writelane_b32 v234, s48, 48
	v_writelane_b32 v234, s49, 49
	v_writelane_b32 v234, s50, 50
	v_writelane_b32 v234, s51, 51
	v_writelane_b32 v234, s52, 52
	v_writelane_b32 v234, s53, 53
	v_writelane_b32 v234, s54, 54
	v_writelane_b32 v234, s55, 55
	v_writelane_b32 v234, s56, 56
	v_writelane_b32 v234, s57, 57
	v_writelane_b32 v234, s58, 58
	v_writelane_b32 v234, s59, 59
	v_writelane_b32 v234, s60, 60
	v_writelane_b32 v234, s61, 61
	v_writelane_b32 v234, s62, 62
	v_writelane_b32 v234, s63, 63
	v_writelane_b32 v235, s64, 0
	v_writelane_b32 v235, s65, 1
	v_writelane_b32 v235, s66, 2
	v_writelane_b32 v235, s67, 3
	v_writelane_b32 v235, s68, 4
	v_writelane_b32 v235, s69, 5
	v_writelane_b32 v235, s70, 6
	v_writelane_b32 v235, s71, 7
	v_writelane_b32 v235, s72, 8
	v_writelane_b32 v235, s73, 9
	v_writelane_b32 v235, s74, 10
	v_writelane_b32 v235, s75, 11
	v_writelane_b32 v235, s76, 12
	v_writelane_b32 v235, s77, 13
	v_writelane_b32 v235, s78, 14
	v_writelane_b32 v235, s79, 15
	v_writelane_b32 v235, s80, 16
	v_writelane_b32 v235, s81, 17
	v_writelane_b32 v235, s82, 18
	v_writelane_b32 v235, s83, 19
	v_writelane_b32 v235, s84, 20
	v_writelane_b32 v235, s85, 21
	v_writelane_b32 v235, s86, 22
	v_writelane_b32 v235, s87, 23
	v_writelane_b32 v235, s88, 24
	v_writelane_b32 v235, s89, 25
	v_writelane_b32 v235, s90, 26
	v_writelane_b32 v235, s91, 27
	v_writelane_b32 v235, s92, 28
	v_writelane_b32 v235, s93, 29
	v_writelane_b32 v235, s94, 30
	v_writelane_b32 v235, s95, 31
	v_writelane_b32 v235, s96, 32
	v_writelane_b32 v235, s97, 33
	v_writelane_b32 v235, vcc_lo, 34
	v_writelane_b32 v235, vcc_hi, 35
	v_readlane_b32 s72, v233, 47
	v_readlane_b32 s73, v233, 48
	v_readlane_b32 s74, v233, 49
	v_readlane_b32 s75, v233, 50
	v_readlane_b32 s76, v233, 51
	v_readlane_b32 s77, v233, 52
	s_add_u32 s62, s92, 0x400000
	s_addc_u32 s63, s93, 0
	v_mov_b32_e32 v1, v210
	s_nop 0
	v_readfirstlane_b32 s0, v1
	v_and_b32_e32 v76, 63, v1
	s_nop 3
	s_ashr_i32 s8, s0, 6
	s_lshr_b32 s1, s2, 1
	s_lshl_b32 s1, s1, 0
	s_and_b32 s3, s2, 0
	s_or_b32 s1, s1, s3
	s_lshl_b32 s1, s1, 3
	s_add_i32 s26, s8, s1
	s_addk_i32 s26, 0x1c80
	s_movk_i32 s96, 0x400
	s_movk_i32 s101, 0x247f
	s_mov_b32 s100, 2
	s_branch .Lp0_setup

.LBB0_399:
	ds_read_b128 v[88:91], v215
	ds_read_b128 v[92:95], v215 offset:1024
	ds_read_b128 v[128:131], v215 offset:2048
	ds_read_b128 v[132:135], v215 offset:3072
	ds_read_b128 v[136:139], v216
	ds_read_b128 v[140:143], v216 offset:1024
	ds_read_b128 v[152:155], v216 offset:2048
	ds_read_b128 v[156:159], v216 offset:3072
	s_add_u32 s12, s4, 0x100
	s_addc_u32 s13, s5, 0
	s_cmp_eq_u32 s82, 20
	s_cselect_b32 s47, s41, s13
	s_cselect_b32 s46, s40, s12
	s_cselect_b32 s15, s45, s81
	s_cselect_b32 s14, s44, s80
	v_lshl_add_u64 v[208:209], s[4:5], 0, v[176:177]
	s_add_i32 m0, s50, 0xc000
	ds_read_b128 v[160:163], v217
	ds_read_b128 v[164:167], v217 offset:1024
	ds_read_b128 v[184:187], v217 offset:2048
	ds_read_b128 v[188:191], v217 offset:3072
	ds_read_b128 v[192:195], v217 offset:4096
	ds_read_b128 v[196:199], v217 offset:5120
	ds_read_b128 v[200:203], v217 offset:6144
	ds_read_b128 v[204:207], v217 offset:7168
	global_load_lds_dwordx4 v[208:209], off
	v_lshl_add_u64 v[208:209], s[4:5], 0, v[178:179]
	s_add_i32 m0, s50, 0xe000
	s_nop 0
	global_load_lds_dwordx4 v[208:209], off
	s_waitcnt vmcnt(8)
	s_waitcnt lgkmcnt(0)
	s_barrier
	s_waitcnt lgkmcnt(0)
	v_mfma_f32_16x16x32_bf16 v[148:151], v[88:91], v[160:163], v[148:151]
	v_mfma_f32_16x16x32_bf16 v[144:147], v[128:131], v[160:163], v[144:147]
	v_mfma_f32_16x16x32_bf16 v[124:127], v[88:91], v[184:187], v[124:127]
	v_mfma_f32_16x16x32_bf16 v[120:123], v[128:131], v[184:187], v[120:123]
	v_mfma_f32_16x16x32_bf16 v[116:119], v[88:91], v[192:195], v[116:119]
	v_mfma_f32_16x16x32_bf16 v[112:115], v[128:131], v[192:195], v[112:115]
	v_mfma_f32_16x16x32_bf16 v[108:111], v[88:91], v[200:203], v[108:111]
	v_mfma_f32_16x16x32_bf16 v[104:107], v[128:131], v[200:203], v[104:107]
	v_mfma_f32_16x16x32_bf16 v[148:151], v[92:95], v[164:167], v[148:151]
	v_mfma_f32_16x16x32_bf16 v[144:147], v[132:135], v[164:167], v[144:147]
	v_mfma_f32_16x16x32_bf16 v[124:127], v[92:95], v[188:191], v[124:127]
	v_mfma_f32_16x16x32_bf16 v[120:123], v[132:135], v[188:191], v[120:123]
	v_mfma_f32_16x16x32_bf16 v[116:119], v[92:95], v[196:199], v[116:119]
	v_mfma_f32_16x16x32_bf16 v[112:115], v[132:135], v[196:199], v[112:115]
	v_mfma_f32_16x16x32_bf16 v[108:111], v[92:95], v[204:207], v[108:111]
	v_mfma_f32_16x16x32_bf16 v[104:107], v[132:135], v[204:207], v[104:107]
	v_mfma_f32_16x16x32_bf16 v[60:63], v[136:139], v[160:163], v[60:63]
	v_mfma_f32_16x16x32_bf16 v[56:59], v[152:155], v[160:163], v[56:59]
	v_mfma_f32_16x16x32_bf16 v[52:55], v[136:139], v[184:187], v[52:55]
	v_mfma_f32_16x16x32_bf16 v[48:51], v[152:155], v[184:187], v[48:51]
	v_mfma_f32_16x16x32_bf16 v[44:47], v[136:139], v[192:195], v[44:47]
	v_mfma_f32_16x16x32_bf16 v[40:43], v[152:155], v[192:195], v[40:43]
	v_mfma_f32_16x16x32_bf16 v[36:39], v[136:139], v[200:203], v[36:39]
	v_mfma_f32_16x16x32_bf16 v[32:35], v[152:155], v[200:203], v[32:35]
	v_mfma_f32_16x16x32_bf16 v[60:63], v[140:143], v[164:167], v[60:63]
	v_mfma_f32_16x16x32_bf16 v[56:59], v[156:159], v[164:167], v[56:59]
	v_mfma_f32_16x16x32_bf16 v[52:55], v[140:143], v[188:191], v[52:55]
	v_mfma_f32_16x16x32_bf16 v[48:51], v[156:159], v[188:191], v[48:51]
	v_mfma_f32_16x16x32_bf16 v[44:47], v[140:143], v[196:199], v[44:47]
	v_mfma_f32_16x16x32_bf16 v[40:43], v[156:159], v[196:199], v[40:43]
	v_mfma_f32_16x16x32_bf16 v[36:39], v[140:143], v[204:207], v[36:39]
	v_mfma_f32_16x16x32_bf16 v[32:35], v[156:159], v[204:207], v[32:35]
	s_barrier
	s_add_i32 s4, s65, s49
	v_lshl_add_u64 v[208:209], s[14:15], 0, v[172:173]
	s_mov_b32 m0, s4
	ds_read_b128 v[160:163], v217 offset:16384
	ds_read_b128 v[164:167], v217 offset:17408
	ds_read_b128 v[184:187], v217 offset:18432
	ds_read_b128 v[188:191], v217 offset:19456
	ds_read_b128 v[192:195], v217 offset:20480
	ds_read_b128 v[196:199], v217 offset:21504
	ds_read_b128 v[200:203], v217 offset:22528
	ds_read_b128 v[204:207], v217 offset:23552
	global_load_lds_dwordx4 v[208:209], off
	s_add_i32 m0, s4, 0x2000
	s_add_u32 s4, s14, 0x60000
	v_lshl_add_u64 v[218:219], s[14:15], 0, v[168:169]
	s_addc_u32 s5, s15, 0
	s_add_i32 s24, s66, s49
	global_load_lds_dwordx4 v[218:219], off
	v_lshl_add_u64 v[220:221], s[4:5], 0, v[172:173]
	s_mov_b32 m0, s24
	v_lshl_add_u64 v[222:223], s[46:47], 0, v[170:171]
	global_load_lds_dwordx4 v[220:221], off
	v_lshl_add_u64 v[220:221], s[4:5], 0, v[168:169]
	s_add_i32 m0, s24, 0x2000
	s_nop 0
	global_load_lds_dwordx4 v[220:221], off
	v_lshl_add_u64 v[220:221], s[46:47], 0, v[174:175]
	s_mov_b32 m0, s50
	s_nop 0
	global_load_lds_dwordx4 v[220:221], off
	s_mov_b32 m0, s51
	s_nop 0
	global_load_lds_dwordx4 v[222:223], off
	s_waitcnt vmcnt(8)
	s_waitcnt lgkmcnt(0)
	s_barrier
	s_waitcnt lgkmcnt(0)
	v_mfma_f32_16x16x32_bf16 v[100:103], v[88:91], v[160:163], v[100:103]
	v_mfma_f32_16x16x32_bf16 v[96:99], v[128:131], v[160:163], v[96:99]
	v_mfma_f32_16x16x32_bf16 v[84:87], v[88:91], v[184:187], v[84:87]
	v_mfma_f32_16x16x32_bf16 v[80:83], v[128:131], v[184:187], v[80:83]
	v_mfma_f32_16x16x32_bf16 v[76:79], v[88:91], v[192:195], v[76:79]
	v_mfma_f32_16x16x32_bf16 v[72:75], v[128:131], v[192:195], v[72:75]
	v_mfma_f32_16x16x32_bf16 v[68:71], v[88:91], v[200:203], v[68:71]
	v_mfma_f32_16x16x32_bf16 v[64:67], v[128:131], v[200:203], v[64:67]
	v_mfma_f32_16x16x32_bf16 v[100:103], v[92:95], v[164:167], v[100:103]
	v_mfma_f32_16x16x32_bf16 v[96:99], v[132:135], v[164:167], v[96:99]
	v_mfma_f32_16x16x32_bf16 v[84:87], v[92:95], v[188:191], v[84:87]
	v_mfma_f32_16x16x32_bf16 v[80:83], v[132:135], v[188:191], v[80:83]
	v_mfma_f32_16x16x32_bf16 v[76:79], v[92:95], v[196:199], v[76:79]
	v_mfma_f32_16x16x32_bf16 v[72:75], v[132:135], v[196:199], v[72:75]
	v_mfma_f32_16x16x32_bf16 v[68:71], v[92:95], v[204:207], v[68:71]
	v_mfma_f32_16x16x32_bf16 v[64:67], v[132:135], v[204:207], v[64:67]
	v_mfma_f32_16x16x32_bf16 v[28:31], v[136:139], v[160:163], v[28:31]
	v_mfma_f32_16x16x32_bf16 v[24:27], v[152:155], v[160:163], v[24:27]
	v_mfma_f32_16x16x32_bf16 v[20:23], v[136:139], v[184:187], v[20:23]
	v_mfma_f32_16x16x32_bf16 v[16:19], v[152:155], v[184:187], v[16:19]
	v_mfma_f32_16x16x32_bf16 v[12:15], v[136:139], v[192:195], v[12:15]
	v_mfma_f32_16x16x32_bf16 v[8:11], v[152:155], v[192:195], v[8:11]
	v_mfma_f32_16x16x32_bf16 v[4:7], v[136:139], v[200:203], v[4:7]
	v_mfma_f32_16x16x32_bf16 v[0:3], v[152:155], v[200:203], v[0:3]
	v_mfma_f32_16x16x32_bf16 v[28:31], v[140:143], v[164:167], v[28:31]
	v_mfma_f32_16x16x32_bf16 v[24:27], v[156:159], v[164:167], v[24:27]
	v_mfma_f32_16x16x32_bf16 v[20:23], v[140:143], v[188:191], v[20:23]
	v_mfma_f32_16x16x32_bf16 v[16:19], v[156:159], v[188:191], v[16:19]
	v_mfma_f32_16x16x32_bf16 v[12:15], v[140:143], v[196:199], v[12:15]
	v_mfma_f32_16x16x32_bf16 v[8:11], v[156:159], v[196:199], v[8:11]
	v_mfma_f32_16x16x32_bf16 v[4:7], v[140:143], v[204:207], v[4:7]
	v_mfma_f32_16x16x32_bf16 v[0:3], v[156:159], v[204:207], v[0:3]
	s_barrier
	s_add_i32 s24, 0, 0x18000
	s_add_i32 s25, 0, 0x1c000
	v_add_u32_e32 v132, s24, v213
	v_add_u32_e32 v156, s25, v213
	ds_read_b128 v[88:91], v132
	ds_read_b128 v[92:95], v132 offset:1024
	ds_read_b128 v[128:131], v132 offset:2048
	ds_read_b128 v[132:135], v132 offset:3072
	ds_read_b128 v[136:139], v156
	ds_read_b128 v[140:143], v156 offset:1024
	ds_read_b128 v[152:155], v156 offset:2048
	ds_read_b128 v[156:159], v156 offset:3072
	s_add_u32 s4, s46, 0x60000
	s_addc_u32 s5, s47, 0
	s_mov_b32 m0, s52
	v_lshl_add_u64 v[224:225], s[4:5], 0, v[174:175]
	ds_read_b128 v[160:163], v217 offset:32768
	ds_read_b128 v[164:167], v217 offset:33792
	ds_read_b128 v[184:187], v217 offset:34816
	ds_read_b128 v[188:191], v217 offset:35840
	ds_read_b128 v[192:195], v217 offset:36864
	ds_read_b128 v[196:199], v217 offset:37888
	ds_read_b128 v[200:203], v217 offset:38912
	ds_read_b128 v[204:207], v217 offset:39936
	global_load_lds_dwordx4 v[224:225], off
	v_lshl_add_u64 v[224:225], s[4:5], 0, v[170:171]
	s_mov_b32 m0, s53
	s_nop 0
	global_load_lds_dwordx4 v[224:225], off
	s_waitcnt vmcnt(8)
	s_waitcnt lgkmcnt(0)
	s_barrier
	s_waitcnt lgkmcnt(0)
	v_mfma_f32_16x16x32_bf16 v[148:151], v[88:91], v[160:163], v[148:151]
	v_mfma_f32_16x16x32_bf16 v[144:147], v[128:131], v[160:163], v[144:147]
	v_mfma_f32_16x16x32_bf16 v[124:127], v[88:91], v[184:187], v[124:127]
	v_mfma_f32_16x16x32_bf16 v[120:123], v[128:131], v[184:187], v[120:123]
	v_mfma_f32_16x16x32_bf16 v[116:119], v[88:91], v[192:195], v[116:119]
	v_mfma_f32_16x16x32_bf16 v[112:115], v[128:131], v[192:195], v[112:115]
	v_mfma_f32_16x16x32_bf16 v[108:111], v[88:91], v[200:203], v[108:111]
	v_mfma_f32_16x16x32_bf16 v[104:107], v[128:131], v[200:203], v[104:107]
	v_mfma_f32_16x16x32_bf16 v[148:151], v[92:95], v[164:167], v[148:151]
	v_mfma_f32_16x16x32_bf16 v[144:147], v[132:135], v[164:167], v[144:147]
	v_mfma_f32_16x16x32_bf16 v[124:127], v[92:95], v[188:191], v[124:127]
	v_mfma_f32_16x16x32_bf16 v[120:123], v[132:135], v[188:191], v[120:123]
	v_mfma_f32_16x16x32_bf16 v[116:119], v[92:95], v[196:199], v[116:119]
	v_mfma_f32_16x16x32_bf16 v[112:115], v[132:135], v[196:199], v[112:115]
	v_mfma_f32_16x16x32_bf16 v[108:111], v[92:95], v[204:207], v[108:111]
	v_mfma_f32_16x16x32_bf16 v[104:107], v[132:135], v[204:207], v[104:107]
	v_mfma_f32_16x16x32_bf16 v[60:63], v[136:139], v[160:163], v[60:63]
	v_mfma_f32_16x16x32_bf16 v[56:59], v[152:155], v[160:163], v[56:59]
	v_mfma_f32_16x16x32_bf16 v[52:55], v[136:139], v[184:187], v[52:55]
	v_mfma_f32_16x16x32_bf16 v[48:51], v[152:155], v[184:187], v[48:51]
	v_mfma_f32_16x16x32_bf16 v[44:47], v[136:139], v[192:195], v[44:47]
	v_mfma_f32_16x16x32_bf16 v[40:43], v[152:155], v[192:195], v[40:43]
	v_mfma_f32_16x16x32_bf16 v[36:39], v[136:139], v[200:203], v[36:39]
	v_mfma_f32_16x16x32_bf16 v[32:35], v[152:155], v[200:203], v[32:35]
	v_mfma_f32_16x16x32_bf16 v[60:63], v[140:143], v[164:167], v[60:63]
	v_mfma_f32_16x16x32_bf16 v[56:59], v[156:159], v[164:167], v[56:59]
	v_mfma_f32_16x16x32_bf16 v[52:55], v[140:143], v[188:191], v[52:55]
	v_mfma_f32_16x16x32_bf16 v[48:51], v[156:159], v[188:191], v[48:51]
	v_mfma_f32_16x16x32_bf16 v[44:47], v[140:143], v[196:199], v[44:47]
	v_mfma_f32_16x16x32_bf16 v[40:43], v[156:159], v[196:199], v[40:43]
	v_mfma_f32_16x16x32_bf16 v[36:39], v[140:143], v[204:207], v[36:39]
	v_mfma_f32_16x16x32_bf16 v[32:35], v[156:159], v[204:207], v[32:35]
	s_barrier
	s_add_i32 s4, s24, s49
	v_lshl_add_u64 v[208:209], v[208:209], 0, s[22:23]
	s_mov_b32 m0, s4
	ds_read_b128 v[160:163], v217 offset:49152
	ds_read_b128 v[164:167], v217 offset:50176
	ds_read_b128 v[184:187], v217 offset:51200
	ds_read_b128 v[188:191], v217 offset:52224
	ds_read_b128 v[192:195], v217 offset:53248
	ds_read_b128 v[196:199], v217 offset:54272
	ds_read_b128 v[200:203], v217 offset:55296
	ds_read_b128 v[204:207], v217 offset:56320
	global_load_lds_dwordx4 v[208:209], off
	s_add_i32 m0, s4, 0x2000
	s_add_u32 s4, s14, 0x60080
	v_lshl_add_u64 v[208:209], v[218:219], 0, s[22:23]
	s_addc_u32 s5, s15, 0
	s_add_i32 s14, s25, s49
	global_load_lds_dwordx4 v[208:209], off
	v_lshl_add_u64 v[208:209], s[4:5], 0, v[172:173]
	s_mov_b32 m0, s14
	s_nop 0
	global_load_lds_dwordx4 v[208:209], off
	v_lshl_add_u64 v[208:209], s[4:5], 0, v[168:169]
	s_add_i32 m0, s14, 0x2000
	s_nop 0
	global_load_lds_dwordx4 v[208:209], off
	v_lshl_add_u64 v[208:209], v[220:221], 0, s[22:23]
	s_mov_b32 m0, s63
	s_nop 0
	global_load_lds_dwordx4 v[208:209], off
	v_lshl_add_u64 v[208:209], v[222:223], 0, s[22:23]
	s_mov_b32 m0, s64
	s_nop 0
	global_load_lds_dwordx4 v[208:209], off
	s_waitcnt vmcnt(8)
	s_waitcnt lgkmcnt(0)
	s_barrier
	s_waitcnt lgkmcnt(0)
	v_mfma_f32_16x16x32_bf16 v[100:103], v[88:91], v[160:163], v[100:103]
	v_mfma_f32_16x16x32_bf16 v[96:99], v[128:131], v[160:163], v[96:99]
	v_mfma_f32_16x16x32_bf16 v[84:87], v[88:91], v[184:187], v[84:87]
	v_mfma_f32_16x16x32_bf16 v[80:83], v[128:131], v[184:187], v[80:83]
	v_mfma_f32_16x16x32_bf16 v[76:79], v[88:91], v[192:195], v[76:79]
	v_mfma_f32_16x16x32_bf16 v[72:75], v[128:131], v[192:195], v[72:75]
	v_mfma_f32_16x16x32_bf16 v[68:71], v[88:91], v[200:203], v[68:71]
	v_mfma_f32_16x16x32_bf16 v[64:67], v[128:131], v[200:203], v[64:67]
	v_mfma_f32_16x16x32_bf16 v[100:103], v[92:95], v[164:167], v[100:103]
	v_mfma_f32_16x16x32_bf16 v[96:99], v[132:135], v[164:167], v[96:99]
	v_mfma_f32_16x16x32_bf16 v[84:87], v[92:95], v[188:191], v[84:87]
	v_mfma_f32_16x16x32_bf16 v[80:83], v[132:135], v[188:191], v[80:83]
	v_mfma_f32_16x16x32_bf16 v[76:79], v[92:95], v[196:199], v[76:79]
	v_mfma_f32_16x16x32_bf16 v[72:75], v[132:135], v[196:199], v[72:75]
	v_mfma_f32_16x16x32_bf16 v[68:71], v[92:95], v[204:207], v[68:71]
	v_mfma_f32_16x16x32_bf16 v[64:67], v[132:135], v[204:207], v[64:67]
	v_mfma_f32_16x16x32_bf16 v[28:31], v[136:139], v[160:163], v[28:31]
	v_mfma_f32_16x16x32_bf16 v[24:27], v[152:155], v[160:163], v[24:27]
	v_mfma_f32_16x16x32_bf16 v[20:23], v[136:139], v[184:187], v[20:23]
	v_mfma_f32_16x16x32_bf16 v[16:19], v[152:155], v[184:187], v[16:19]
	v_mfma_f32_16x16x32_bf16 v[12:15], v[136:139], v[192:195], v[12:15]
	v_mfma_f32_16x16x32_bf16 v[8:11], v[152:155], v[192:195], v[8:11]
	v_mfma_f32_16x16x32_bf16 v[4:7], v[136:139], v[200:203], v[4:7]
	v_mfma_f32_16x16x32_bf16 v[0:3], v[152:155], v[200:203], v[0:3]
	v_mfma_f32_16x16x32_bf16 v[28:31], v[140:143], v[164:167], v[28:31]
	v_mfma_f32_16x16x32_bf16 v[24:27], v[156:159], v[164:167], v[24:27]
	v_mfma_f32_16x16x32_bf16 v[20:23], v[140:143], v[188:191], v[20:23]
	v_mfma_f32_16x16x32_bf16 v[16:19], v[156:159], v[188:191], v[16:19]
	v_mfma_f32_16x16x32_bf16 v[12:15], v[140:143], v[196:199], v[12:15]
	v_mfma_f32_16x16x32_bf16 v[8:11], v[156:159], v[196:199], v[8:11]
	v_mfma_f32_16x16x32_bf16 v[4:7], v[140:143], v[204:207], v[4:7]
	v_mfma_f32_16x16x32_bf16 v[0:3], v[156:159], v[204:207], v[0:3]
	s_barrier
	s_add_i32 s82, s82, 2
	s_add_u32 s80, s80, 0x100
	s_addc_u32 s81, s81, 0
	s_cmp_gt_u32 s82, 21
	s_mov_b64 s[4:5], s[12:13]
	s_cbranch_scc0 .LBB0_399
	s_mov_b64 s[24:25], s[74:75]
	s_mov_b64 s[14:15], s[72:73]
	s_and_b64 vcc, exec, s[42:43]
	s_cbranch_vccz .LBB0_402
	s_barrier

.LBB0_423:
	ds_read_b128 v[156:159], v151
	ds_read_b128 v[160:163], v151 offset:1024
	ds_read_b128 v[164:167], v151 offset:2048
	ds_read_b128 v[168:171], v151 offset:3072
	ds_read_b128 v[172:175], v153
	ds_read_b128 v[176:179], v153 offset:1024
	ds_read_b128 v[180:183], v153 offset:2048
	ds_read_b128 v[184:187], v153 offset:3072
	s_add_u32 s14, s12, 0xfff80080
	s_addc_u32 s15, s13, -1
	s_cmp_eq_u32 s89, 28
	s_cselect_b32 s57, s49, s15
	s_cselect_b32 s56, s85, s14
	s_cselect_b32 s15, s45, s88
	s_cselect_b32 s14, s86, s87
	v_lshl_add_u64 v[208:209], s[12:13], 0, v[142:143]
	s_add_i32 m0, s67, 0xc000
	ds_read_b128 v[188:191], v155
	ds_read_b128 v[192:195], v155 offset:1024
	ds_read_b128 v[196:199], v155 offset:2048
	ds_read_b128 v[200:203], v155 offset:3072
	ds_read_b128 v[204:207], v155 offset:4096
	ds_read_b128 v[212:215], v155 offset:5120
	ds_read_b128 v[216:219], v155 offset:6144
	ds_read_b128 v[220:223], v155 offset:7168
	global_load_lds_dwordx4 v[208:209], off
	v_lshl_add_u64 v[208:209], s[12:13], 0, v[144:145]
	s_add_i32 m0, s67, 0xe000
	s_nop 0
	global_load_lds_dwordx4 v[208:209], off
	s_waitcnt vmcnt(8)
	s_waitcnt lgkmcnt(0)
	s_barrier
	s_waitcnt lgkmcnt(0)
	v_mfma_f32_16x16x32_bf16 v[124:127], v[156:159], v[188:191], v[124:127]
	v_mfma_f32_16x16x32_bf16 v[120:123], v[164:167], v[188:191], v[120:123]
	v_mfma_f32_16x16x32_bf16 v[116:119], v[156:159], v[196:199], v[116:119]
	v_mfma_f32_16x16x32_bf16 v[112:115], v[164:167], v[196:199], v[112:115]
	v_mfma_f32_16x16x32_bf16 v[108:111], v[156:159], v[204:207], v[108:111]
	v_mfma_f32_16x16x32_bf16 v[104:107], v[164:167], v[204:207], v[104:107]
	v_mfma_f32_16x16x32_bf16 v[100:103], v[156:159], v[216:219], v[100:103]
	v_mfma_f32_16x16x32_bf16 v[96:99], v[164:167], v[216:219], v[96:99]
	v_mfma_f32_16x16x32_bf16 v[124:127], v[160:163], v[192:195], v[124:127]
	v_mfma_f32_16x16x32_bf16 v[120:123], v[168:171], v[192:195], v[120:123]
	v_mfma_f32_16x16x32_bf16 v[116:119], v[160:163], v[200:203], v[116:119]
	v_mfma_f32_16x16x32_bf16 v[112:115], v[168:171], v[200:203], v[112:115]
	v_mfma_f32_16x16x32_bf16 v[108:111], v[160:163], v[212:215], v[108:111]
	v_mfma_f32_16x16x32_bf16 v[104:107], v[168:171], v[212:215], v[104:107]
	v_mfma_f32_16x16x32_bf16 v[100:103], v[160:163], v[220:223], v[100:103]
	v_mfma_f32_16x16x32_bf16 v[96:99], v[168:171], v[220:223], v[96:99]
	v_mfma_f32_16x16x32_bf16 v[68:71], v[172:175], v[188:191], v[68:71]
	v_mfma_f32_16x16x32_bf16 v[60:63], v[180:183], v[188:191], v[60:63]
	v_mfma_f32_16x16x32_bf16 v[52:55], v[172:175], v[196:199], v[52:55]
	v_mfma_f32_16x16x32_bf16 v[48:51], v[180:183], v[196:199], v[48:51]
	v_mfma_f32_16x16x32_bf16 v[44:47], v[172:175], v[204:207], v[44:47]
	v_mfma_f32_16x16x32_bf16 v[40:43], v[180:183], v[204:207], v[40:43]
	v_mfma_f32_16x16x32_bf16 v[36:39], v[172:175], v[216:219], v[36:39]
	v_mfma_f32_16x16x32_bf16 v[32:35], v[180:183], v[216:219], v[32:35]
	v_mfma_f32_16x16x32_bf16 v[68:71], v[176:179], v[192:195], v[68:71]
	v_mfma_f32_16x16x32_bf16 v[60:63], v[184:187], v[192:195], v[60:63]
	v_mfma_f32_16x16x32_bf16 v[52:55], v[176:179], v[200:203], v[52:55]
	v_mfma_f32_16x16x32_bf16 v[48:51], v[184:187], v[200:203], v[48:51]
	v_mfma_f32_16x16x32_bf16 v[44:47], v[176:179], v[212:215], v[44:47]
	v_mfma_f32_16x16x32_bf16 v[40:43], v[184:187], v[212:215], v[40:43]
	v_mfma_f32_16x16x32_bf16 v[36:39], v[176:179], v[220:223], v[36:39]
	v_mfma_f32_16x16x32_bf16 v[32:35], v[184:187], v[220:223], v[32:35]
	s_barrier
	s_add_i32 s24, s81, s66
	v_lshl_add_u64 v[208:209], s[14:15], 0, v[130:131]
	s_mov_b32 m0, s24
	ds_read_b128 v[188:191], v155 offset:16384
	ds_read_b128 v[192:195], v155 offset:17408
	ds_read_b128 v[196:199], v155 offset:18432
	ds_read_b128 v[200:203], v155 offset:19456
	ds_read_b128 v[204:207], v155 offset:20480
	ds_read_b128 v[212:215], v155 offset:21504
	ds_read_b128 v[216:219], v155 offset:22528
	ds_read_b128 v[220:223], v155 offset:23552
	global_load_lds_dwordx4 v[208:209], off
	s_add_i32 m0, s24, 0x2000
	s_add_u32 s24, s14, 0x80000
	v_lshl_add_u64 v[224:225], s[14:15], 0, v[134:135]
	s_addc_u32 s25, s15, 0
	s_add_i32 s26, s82, s66
	global_load_lds_dwordx4 v[224:225], off
	v_lshl_add_u64 v[226:227], s[24:25], 0, v[130:131]
	s_mov_b32 m0, s26
	v_lshl_add_u64 v[228:229], s[56:57], 0, v[132:133]
	global_load_lds_dwordx4 v[226:227], off
	v_lshl_add_u64 v[226:227], s[24:25], 0, v[134:135]
	s_add_i32 m0, s26, 0x2000
	s_nop 0
	global_load_lds_dwordx4 v[226:227], off
	v_lshl_add_u64 v[226:227], s[56:57], 0, v[128:129]
	s_mov_b32 m0, s67
	s_nop 0
	global_load_lds_dwordx4 v[226:227], off
	s_mov_b32 m0, s68
	s_nop 0
	global_load_lds_dwordx4 v[228:229], off
	s_waitcnt vmcnt(8)
	s_waitcnt lgkmcnt(0)
	s_barrier
	s_waitcnt lgkmcnt(0)
	v_mfma_f32_16x16x32_bf16 v[92:95], v[156:159], v[188:191], v[92:95]
	v_mfma_f32_16x16x32_bf16 v[88:91], v[164:167], v[188:191], v[88:91]
	v_mfma_f32_16x16x32_bf16 v[84:87], v[156:159], v[196:199], v[84:87]
	v_mfma_f32_16x16x32_bf16 v[80:83], v[164:167], v[196:199], v[80:83]
	v_mfma_f32_16x16x32_bf16 v[76:79], v[156:159], v[204:207], v[76:79]
	v_mfma_f32_16x16x32_bf16 v[72:75], v[164:167], v[204:207], v[72:75]
	v_mfma_f32_16x16x32_bf16 v[64:67], v[156:159], v[216:219], v[64:67]
	v_mfma_f32_16x16x32_bf16 v[56:59], v[164:167], v[216:219], v[56:59]
	v_mfma_f32_16x16x32_bf16 v[92:95], v[160:163], v[192:195], v[92:95]
	v_mfma_f32_16x16x32_bf16 v[88:91], v[168:171], v[192:195], v[88:91]
	v_mfma_f32_16x16x32_bf16 v[84:87], v[160:163], v[200:203], v[84:87]
	v_mfma_f32_16x16x32_bf16 v[80:83], v[168:171], v[200:203], v[80:83]
	v_mfma_f32_16x16x32_bf16 v[76:79], v[160:163], v[212:215], v[76:79]
	v_mfma_f32_16x16x32_bf16 v[72:75], v[168:171], v[212:215], v[72:75]
	v_mfma_f32_16x16x32_bf16 v[64:67], v[160:163], v[220:223], v[64:67]
	v_mfma_f32_16x16x32_bf16 v[56:59], v[168:171], v[220:223], v[56:59]
	v_mfma_f32_16x16x32_bf16 v[28:31], v[172:175], v[188:191], v[28:31]
	v_mfma_f32_16x16x32_bf16 v[24:27], v[180:183], v[188:191], v[24:27]
	v_mfma_f32_16x16x32_bf16 v[20:23], v[172:175], v[196:199], v[20:23]
	v_mfma_f32_16x16x32_bf16 v[16:19], v[180:183], v[196:199], v[16:19]
	v_mfma_f32_16x16x32_bf16 v[12:15], v[172:175], v[204:207], v[12:15]
	v_mfma_f32_16x16x32_bf16 v[8:11], v[180:183], v[204:207], v[8:11]
	v_mfma_f32_16x16x32_bf16 v[4:7], v[172:175], v[216:219], v[4:7]
	v_mfma_f32_16x16x32_bf16 v[0:3], v[180:183], v[216:219], v[0:3]
	v_mfma_f32_16x16x32_bf16 v[28:31], v[176:179], v[192:195], v[28:31]
	v_mfma_f32_16x16x32_bf16 v[24:27], v[184:187], v[192:195], v[24:27]
	v_mfma_f32_16x16x32_bf16 v[20:23], v[176:179], v[200:203], v[20:23]
	v_mfma_f32_16x16x32_bf16 v[16:19], v[184:187], v[200:203], v[16:19]
	v_mfma_f32_16x16x32_bf16 v[12:15], v[176:179], v[212:215], v[12:15]
	v_mfma_f32_16x16x32_bf16 v[8:11], v[184:187], v[212:215], v[8:11]
	v_mfma_f32_16x16x32_bf16 v[4:7], v[176:179], v[220:223], v[4:7]
	v_mfma_f32_16x16x32_bf16 v[0:3], v[184:187], v[220:223], v[0:3]
	s_barrier
	s_add_i32 s26, 0, 0x18000
	v_add_u32_e32 v136, s26, v149
	s_add_i32 s27, 0, 0x1c000
	ds_read_b128 v[156:159], v136
	ds_read_b128 v[160:163], v136 offset:1024
	ds_read_b128 v[164:167], v136 offset:2048
	ds_read_b128 v[168:171], v136 offset:3072
	v_add_u32_e32 v136, s27, v149
	ds_read_b128 v[172:175], v136
	ds_read_b128 v[176:179], v136 offset:1024
	ds_read_b128 v[180:183], v136 offset:2048
	ds_read_b128 v[184:187], v136 offset:3072
	s_add_u32 s24, s56, 0x80000
	s_addc_u32 s25, s57, 0
	s_mov_b32 m0, s69
	v_lshl_add_u64 v[230:231], s[24:25], 0, v[128:129]
	ds_read_b128 v[188:191], v155 offset:32768
	ds_read_b128 v[192:195], v155 offset:33792
	ds_read_b128 v[196:199], v155 offset:34816
	ds_read_b128 v[200:203], v155 offset:35840
	ds_read_b128 v[204:207], v155 offset:36864
	ds_read_b128 v[212:215], v155 offset:37888
	ds_read_b128 v[216:219], v155 offset:38912
	ds_read_b128 v[220:223], v155 offset:39936
	global_load_lds_dwordx4 v[230:231], off
	v_lshl_add_u64 v[230:231], s[24:25], 0, v[132:133]
	s_mov_b32 m0, s76
	s_nop 0
	global_load_lds_dwordx4 v[230:231], off
	s_waitcnt vmcnt(8)
	s_waitcnt lgkmcnt(0)
	s_barrier
	s_waitcnt lgkmcnt(0)
	v_mfma_f32_16x16x32_bf16 v[124:127], v[156:159], v[188:191], v[124:127]
	v_mfma_f32_16x16x32_bf16 v[120:123], v[164:167], v[188:191], v[120:123]
	v_mfma_f32_16x16x32_bf16 v[116:119], v[156:159], v[196:199], v[116:119]
	v_mfma_f32_16x16x32_bf16 v[112:115], v[164:167], v[196:199], v[112:115]
	v_mfma_f32_16x16x32_bf16 v[108:111], v[156:159], v[204:207], v[108:111]
	v_mfma_f32_16x16x32_bf16 v[104:107], v[164:167], v[204:207], v[104:107]
	v_mfma_f32_16x16x32_bf16 v[100:103], v[156:159], v[216:219], v[100:103]
	v_mfma_f32_16x16x32_bf16 v[96:99], v[164:167], v[216:219], v[96:99]
	v_mfma_f32_16x16x32_bf16 v[124:127], v[160:163], v[192:195], v[124:127]
	v_mfma_f32_16x16x32_bf16 v[120:123], v[168:171], v[192:195], v[120:123]
	v_mfma_f32_16x16x32_bf16 v[116:119], v[160:163], v[200:203], v[116:119]
	v_mfma_f32_16x16x32_bf16 v[112:115], v[168:171], v[200:203], v[112:115]
	v_mfma_f32_16x16x32_bf16 v[108:111], v[160:163], v[212:215], v[108:111]
	v_mfma_f32_16x16x32_bf16 v[104:107], v[168:171], v[212:215], v[104:107]
	v_mfma_f32_16x16x32_bf16 v[100:103], v[160:163], v[220:223], v[100:103]
	v_mfma_f32_16x16x32_bf16 v[96:99], v[168:171], v[220:223], v[96:99]
	v_mfma_f32_16x16x32_bf16 v[68:71], v[172:175], v[188:191], v[68:71]
	v_mfma_f32_16x16x32_bf16 v[60:63], v[180:183], v[188:191], v[60:63]
	v_mfma_f32_16x16x32_bf16 v[52:55], v[172:175], v[196:199], v[52:55]
	v_mfma_f32_16x16x32_bf16 v[48:51], v[180:183], v[196:199], v[48:51]
	v_mfma_f32_16x16x32_bf16 v[44:47], v[172:175], v[204:207], v[44:47]
	v_mfma_f32_16x16x32_bf16 v[40:43], v[180:183], v[204:207], v[40:43]
	v_mfma_f32_16x16x32_bf16 v[36:39], v[172:175], v[216:219], v[36:39]
	v_mfma_f32_16x16x32_bf16 v[32:35], v[180:183], v[216:219], v[32:35]
	v_mfma_f32_16x16x32_bf16 v[68:71], v[176:179], v[192:195], v[68:71]
	v_mfma_f32_16x16x32_bf16 v[60:63], v[184:187], v[192:195], v[60:63]
	v_mfma_f32_16x16x32_bf16 v[52:55], v[176:179], v[200:203], v[52:55]
	v_mfma_f32_16x16x32_bf16 v[48:51], v[184:187], v[200:203], v[48:51]
	v_mfma_f32_16x16x32_bf16 v[44:47], v[176:179], v[212:215], v[44:47]
	v_mfma_f32_16x16x32_bf16 v[40:43], v[184:187], v[212:215], v[40:43]
	v_mfma_f32_16x16x32_bf16 v[36:39], v[176:179], v[220:223], v[36:39]
	v_mfma_f32_16x16x32_bf16 v[32:35], v[184:187], v[220:223], v[32:35]
	s_barrier
	s_add_i32 s24, s26, s66
	v_lshl_add_u64 v[208:209], v[208:209], 0, s[38:39]
	s_mov_b32 m0, s24
	ds_read_b128 v[188:191], v155 offset:49152
	ds_read_b128 v[192:195], v155 offset:50176
	ds_read_b128 v[196:199], v155 offset:51200
	ds_read_b128 v[200:203], v155 offset:52224
	ds_read_b128 v[204:207], v155 offset:53248
	ds_read_b128 v[212:215], v155 offset:54272
	ds_read_b128 v[216:219], v155 offset:55296
	ds_read_b128 v[220:223], v155 offset:56320
	global_load_lds_dwordx4 v[208:209], off
	s_add_i32 m0, s24, 0x2000
	s_add_u32 s14, s14, 0x80080
	v_lshl_add_u64 v[208:209], v[224:225], 0, s[38:39]
	s_addc_u32 s15, s15, 0
	s_add_i32 s24, s27, s66
	global_load_lds_dwordx4 v[208:209], off
	v_lshl_add_u64 v[208:209], s[14:15], 0, v[130:131]
	s_mov_b32 m0, s24
	s_nop 0
	global_load_lds_dwordx4 v[208:209], off
	v_lshl_add_u64 v[208:209], s[14:15], 0, v[134:135]
	s_add_i32 m0, s24, 0x2000
	s_nop 0
	global_load_lds_dwordx4 v[208:209], off
	v_lshl_add_u64 v[208:209], v[226:227], 0, s[38:39]
	s_mov_b32 m0, s77
	s_nop 0
	global_load_lds_dwordx4 v[208:209], off
	v_lshl_add_u64 v[208:209], v[228:229], 0, s[38:39]
	s_mov_b32 m0, s80
	s_nop 0
	global_load_lds_dwordx4 v[208:209], off
	s_waitcnt vmcnt(8)
	s_waitcnt lgkmcnt(0)
	s_barrier
	s_waitcnt lgkmcnt(0)
	v_mfma_f32_16x16x32_bf16 v[92:95], v[156:159], v[188:191], v[92:95]
	v_mfma_f32_16x16x32_bf16 v[88:91], v[164:167], v[188:191], v[88:91]
	v_mfma_f32_16x16x32_bf16 v[84:87], v[156:159], v[196:199], v[84:87]
	v_mfma_f32_16x16x32_bf16 v[80:83], v[164:167], v[196:199], v[80:83]
	v_mfma_f32_16x16x32_bf16 v[76:79], v[156:159], v[204:207], v[76:79]
	v_mfma_f32_16x16x32_bf16 v[72:75], v[164:167], v[204:207], v[72:75]
	v_mfma_f32_16x16x32_bf16 v[64:67], v[156:159], v[216:219], v[64:67]
	v_mfma_f32_16x16x32_bf16 v[56:59], v[164:167], v[216:219], v[56:59]
	v_mfma_f32_16x16x32_bf16 v[92:95], v[160:163], v[192:195], v[92:95]
	v_mfma_f32_16x16x32_bf16 v[88:91], v[168:171], v[192:195], v[88:91]
	v_mfma_f32_16x16x32_bf16 v[84:87], v[160:163], v[200:203], v[84:87]
	v_mfma_f32_16x16x32_bf16 v[80:83], v[168:171], v[200:203], v[80:83]
	v_mfma_f32_16x16x32_bf16 v[76:79], v[160:163], v[212:215], v[76:79]
	v_mfma_f32_16x16x32_bf16 v[72:75], v[168:171], v[212:215], v[72:75]
	v_mfma_f32_16x16x32_bf16 v[64:67], v[160:163], v[220:223], v[64:67]
	v_mfma_f32_16x16x32_bf16 v[56:59], v[168:171], v[220:223], v[56:59]
	v_mfma_f32_16x16x32_bf16 v[28:31], v[172:175], v[188:191], v[28:31]
	v_mfma_f32_16x16x32_bf16 v[24:27], v[180:183], v[188:191], v[24:27]
	v_mfma_f32_16x16x32_bf16 v[20:23], v[172:175], v[196:199], v[20:23]
	v_mfma_f32_16x16x32_bf16 v[16:19], v[180:183], v[196:199], v[16:19]
	v_mfma_f32_16x16x32_bf16 v[12:15], v[172:175], v[204:207], v[12:15]
	v_mfma_f32_16x16x32_bf16 v[8:11], v[180:183], v[204:207], v[8:11]
	v_mfma_f32_16x16x32_bf16 v[4:7], v[172:175], v[216:219], v[4:7]
	v_mfma_f32_16x16x32_bf16 v[0:3], v[180:183], v[216:219], v[0:3]
	v_mfma_f32_16x16x32_bf16 v[28:31], v[176:179], v[192:195], v[28:31]
	v_mfma_f32_16x16x32_bf16 v[24:27], v[184:187], v[192:195], v[24:27]
	v_mfma_f32_16x16x32_bf16 v[20:23], v[176:179], v[200:203], v[20:23]
	v_mfma_f32_16x16x32_bf16 v[16:19], v[184:187], v[200:203], v[16:19]
	v_mfma_f32_16x16x32_bf16 v[12:15], v[176:179], v[212:215], v[12:15]
	v_mfma_f32_16x16x32_bf16 v[8:11], v[184:187], v[212:215], v[8:11]
	v_mfma_f32_16x16x32_bf16 v[4:7], v[176:179], v[220:223], v[4:7]
	v_mfma_f32_16x16x32_bf16 v[0:3], v[184:187], v[220:223], v[0:3]
	s_barrier
	s_add_i32 s89, s89, 2
	s_add_u32 s12, s12, 0x100
	s_addc_u32 s13, s13, 0
	s_add_u32 s87, s87, 0x100
	s_addc_u32 s88, s88, 0
	s_cmp_gt_u32 s89, 29
	s_cbranch_scc0 .LBB0_423
	s_and_b64 vcc, exec, s[40:41]
	s_cbranch_vccz .LBB0_426
	s_barrier

.LBB0_447:
	ds_read_b128 v[156:159], v151
	ds_read_b128 v[160:163], v151 offset:1024
	ds_read_b128 v[164:167], v151 offset:2048
	ds_read_b128 v[168:171], v151 offset:3072
	ds_read_b128 v[172:175], v153
	ds_read_b128 v[176:179], v153 offset:1024
	ds_read_b128 v[180:183], v153 offset:2048
	ds_read_b128 v[184:187], v153 offset:3072
	s_add_u32 s14, s12, 0xfff80080
	s_addc_u32 s15, s13, -1
	s_cmp_eq_u32 s87, 28
	s_cselect_b32 s57, s49, s15
	s_cselect_b32 s56, s83, s14
	s_cselect_b32 s15, s45, s86
	s_cselect_b32 s14, s84, s85
	v_lshl_add_u64 v[208:209], s[12:13], 0, v[142:143]
	s_add_i32 m0, s65, 0xc000
	ds_read_b128 v[188:191], v155
	ds_read_b128 v[192:195], v155 offset:1024
	ds_read_b128 v[196:199], v155 offset:2048
	ds_read_b128 v[200:203], v155 offset:3072
	ds_read_b128 v[204:207], v155 offset:4096
	ds_read_b128 v[212:215], v155 offset:5120
	ds_read_b128 v[216:219], v155 offset:6144
	ds_read_b128 v[220:223], v155 offset:7168
	global_load_lds_dwordx4 v[208:209], off
	v_lshl_add_u64 v[208:209], s[12:13], 0, v[144:145]
	s_add_i32 m0, s65, 0xe000
	s_nop 0
	global_load_lds_dwordx4 v[208:209], off
	s_waitcnt vmcnt(8)
	s_waitcnt lgkmcnt(0)
	s_barrier
	s_waitcnt lgkmcnt(0)
	v_mfma_f32_16x16x32_bf16 v[124:127], v[156:159], v[188:191], v[124:127]
	v_mfma_f32_16x16x32_bf16 v[120:123], v[164:167], v[188:191], v[120:123]
	v_mfma_f32_16x16x32_bf16 v[116:119], v[156:159], v[196:199], v[116:119]
	v_mfma_f32_16x16x32_bf16 v[112:115], v[164:167], v[196:199], v[112:115]
	v_mfma_f32_16x16x32_bf16 v[108:111], v[156:159], v[204:207], v[108:111]
	v_mfma_f32_16x16x32_bf16 v[104:107], v[164:167], v[204:207], v[104:107]
	v_mfma_f32_16x16x32_bf16 v[100:103], v[156:159], v[216:219], v[100:103]
	v_mfma_f32_16x16x32_bf16 v[96:99], v[164:167], v[216:219], v[96:99]
	v_mfma_f32_16x16x32_bf16 v[124:127], v[160:163], v[192:195], v[124:127]
	v_mfma_f32_16x16x32_bf16 v[120:123], v[168:171], v[192:195], v[120:123]
	v_mfma_f32_16x16x32_bf16 v[116:119], v[160:163], v[200:203], v[116:119]
	v_mfma_f32_16x16x32_bf16 v[112:115], v[168:171], v[200:203], v[112:115]
	v_mfma_f32_16x16x32_bf16 v[108:111], v[160:163], v[212:215], v[108:111]
	v_mfma_f32_16x16x32_bf16 v[104:107], v[168:171], v[212:215], v[104:107]
	v_mfma_f32_16x16x32_bf16 v[100:103], v[160:163], v[220:223], v[100:103]
	v_mfma_f32_16x16x32_bf16 v[96:99], v[168:171], v[220:223], v[96:99]
	v_mfma_f32_16x16x32_bf16 v[68:71], v[172:175], v[188:191], v[68:71]
	v_mfma_f32_16x16x32_bf16 v[60:63], v[180:183], v[188:191], v[60:63]
	v_mfma_f32_16x16x32_bf16 v[52:55], v[172:175], v[196:199], v[52:55]
	v_mfma_f32_16x16x32_bf16 v[48:51], v[180:183], v[196:199], v[48:51]
	v_mfma_f32_16x16x32_bf16 v[44:47], v[172:175], v[204:207], v[44:47]
	v_mfma_f32_16x16x32_bf16 v[40:43], v[180:183], v[204:207], v[40:43]
	v_mfma_f32_16x16x32_bf16 v[36:39], v[172:175], v[216:219], v[36:39]
	v_mfma_f32_16x16x32_bf16 v[32:35], v[180:183], v[216:219], v[32:35]
	v_mfma_f32_16x16x32_bf16 v[68:71], v[176:179], v[192:195], v[68:71]
	v_mfma_f32_16x16x32_bf16 v[60:63], v[184:187], v[192:195], v[60:63]
	v_mfma_f32_16x16x32_bf16 v[52:55], v[176:179], v[200:203], v[52:55]
	v_mfma_f32_16x16x32_bf16 v[48:51], v[184:187], v[200:203], v[48:51]
	v_mfma_f32_16x16x32_bf16 v[44:47], v[176:179], v[212:215], v[44:47]
	v_mfma_f32_16x16x32_bf16 v[40:43], v[184:187], v[212:215], v[40:43]
	v_mfma_f32_16x16x32_bf16 v[36:39], v[176:179], v[220:223], v[36:39]
	v_mfma_f32_16x16x32_bf16 v[32:35], v[184:187], v[220:223], v[32:35]
	s_barrier
	s_add_i32 s24, s77, s61
	v_lshl_add_u64 v[208:209], s[14:15], 0, v[130:131]
	s_mov_b32 m0, s24
	ds_read_b128 v[188:191], v155 offset:16384
	ds_read_b128 v[192:195], v155 offset:17408
	ds_read_b128 v[196:199], v155 offset:18432
	ds_read_b128 v[200:203], v155 offset:19456
	ds_read_b128 v[204:207], v155 offset:20480
	ds_read_b128 v[212:215], v155 offset:21504
	ds_read_b128 v[216:219], v155 offset:22528
	ds_read_b128 v[220:223], v155 offset:23552
	global_load_lds_dwordx4 v[208:209], off
	s_add_i32 m0, s24, 0x2000
	s_add_u32 s24, s14, 0x80000
	v_lshl_add_u64 v[224:225], s[14:15], 0, v[134:135]
	s_addc_u32 s25, s15, 0
	s_add_i32 s26, s80, s61
	global_load_lds_dwordx4 v[224:225], off
	v_lshl_add_u64 v[226:227], s[24:25], 0, v[130:131]
	s_mov_b32 m0, s26
	v_lshl_add_u64 v[228:229], s[56:57], 0, v[132:133]
	global_load_lds_dwordx4 v[226:227], off
	v_lshl_add_u64 v[226:227], s[24:25], 0, v[134:135]
	s_add_i32 m0, s26, 0x2000
	s_nop 0
	global_load_lds_dwordx4 v[226:227], off
	v_lshl_add_u64 v[226:227], s[56:57], 0, v[128:129]
	s_mov_b32 m0, s65
	s_nop 0
	global_load_lds_dwordx4 v[226:227], off
	s_mov_b32 m0, s66
	s_nop 0
	global_load_lds_dwordx4 v[228:229], off
	s_waitcnt vmcnt(8)
	s_waitcnt lgkmcnt(0)
	s_barrier
	s_waitcnt lgkmcnt(0)
	v_mfma_f32_16x16x32_bf16 v[92:95], v[156:159], v[188:191], v[92:95]
	v_mfma_f32_16x16x32_bf16 v[88:91], v[164:167], v[188:191], v[88:91]
	v_mfma_f32_16x16x32_bf16 v[84:87], v[156:159], v[196:199], v[84:87]
	v_mfma_f32_16x16x32_bf16 v[80:83], v[164:167], v[196:199], v[80:83]
	v_mfma_f32_16x16x32_bf16 v[76:79], v[156:159], v[204:207], v[76:79]
	v_mfma_f32_16x16x32_bf16 v[72:75], v[164:167], v[204:207], v[72:75]
	v_mfma_f32_16x16x32_bf16 v[64:67], v[156:159], v[216:219], v[64:67]
	v_mfma_f32_16x16x32_bf16 v[56:59], v[164:167], v[216:219], v[56:59]
	v_mfma_f32_16x16x32_bf16 v[92:95], v[160:163], v[192:195], v[92:95]
	v_mfma_f32_16x16x32_bf16 v[88:91], v[168:171], v[192:195], v[88:91]
	v_mfma_f32_16x16x32_bf16 v[84:87], v[160:163], v[200:203], v[84:87]
	v_mfma_f32_16x16x32_bf16 v[80:83], v[168:171], v[200:203], v[80:83]
	v_mfma_f32_16x16x32_bf16 v[76:79], v[160:163], v[212:215], v[76:79]
	v_mfma_f32_16x16x32_bf16 v[72:75], v[168:171], v[212:215], v[72:75]
	v_mfma_f32_16x16x32_bf16 v[64:67], v[160:163], v[220:223], v[64:67]
	v_mfma_f32_16x16x32_bf16 v[56:59], v[168:171], v[220:223], v[56:59]
	v_mfma_f32_16x16x32_bf16 v[28:31], v[172:175], v[188:191], v[28:31]
	v_mfma_f32_16x16x32_bf16 v[24:27], v[180:183], v[188:191], v[24:27]
	v_mfma_f32_16x16x32_bf16 v[20:23], v[172:175], v[196:199], v[20:23]
	v_mfma_f32_16x16x32_bf16 v[16:19], v[180:183], v[196:199], v[16:19]
	v_mfma_f32_16x16x32_bf16 v[12:15], v[172:175], v[204:207], v[12:15]
	v_mfma_f32_16x16x32_bf16 v[8:11], v[180:183], v[204:207], v[8:11]
	v_mfma_f32_16x16x32_bf16 v[4:7], v[172:175], v[216:219], v[4:7]
	v_mfma_f32_16x16x32_bf16 v[0:3], v[180:183], v[216:219], v[0:3]
	v_mfma_f32_16x16x32_bf16 v[28:31], v[176:179], v[192:195], v[28:31]
	v_mfma_f32_16x16x32_bf16 v[24:27], v[184:187], v[192:195], v[24:27]
	v_mfma_f32_16x16x32_bf16 v[20:23], v[176:179], v[200:203], v[20:23]
	v_mfma_f32_16x16x32_bf16 v[16:19], v[184:187], v[200:203], v[16:19]
	v_mfma_f32_16x16x32_bf16 v[12:15], v[176:179], v[212:215], v[12:15]
	v_mfma_f32_16x16x32_bf16 v[8:11], v[184:187], v[212:215], v[8:11]
	v_mfma_f32_16x16x32_bf16 v[4:7], v[176:179], v[220:223], v[4:7]
	v_mfma_f32_16x16x32_bf16 v[0:3], v[184:187], v[220:223], v[0:3]
	s_barrier
	s_add_i32 s26, 0, 0x18000
	v_add_u32_e32 v136, s26, v149
	s_add_i32 s27, 0, 0x1c000
	ds_read_b128 v[156:159], v136
	ds_read_b128 v[160:163], v136 offset:1024
	ds_read_b128 v[164:167], v136 offset:2048
	ds_read_b128 v[168:171], v136 offset:3072
	v_add_u32_e32 v136, s27, v149
	ds_read_b128 v[172:175], v136
	ds_read_b128 v[176:179], v136 offset:1024
	ds_read_b128 v[180:183], v136 offset:2048
	ds_read_b128 v[184:187], v136 offset:3072
	s_add_u32 s24, s56, 0x80000
	s_addc_u32 s25, s57, 0
	s_mov_b32 m0, s67
	v_lshl_add_u64 v[230:231], s[24:25], 0, v[128:129]
	ds_read_b128 v[188:191], v155 offset:32768
	ds_read_b128 v[192:195], v155 offset:33792
	ds_read_b128 v[196:199], v155 offset:34816
	ds_read_b128 v[200:203], v155 offset:35840
	ds_read_b128 v[204:207], v155 offset:36864
	ds_read_b128 v[212:215], v155 offset:37888
	ds_read_b128 v[216:219], v155 offset:38912
	ds_read_b128 v[220:223], v155 offset:39936
	global_load_lds_dwordx4 v[230:231], off
	v_lshl_add_u64 v[230:231], s[24:25], 0, v[132:133]
	s_mov_b32 m0, s68
	s_nop 0
	global_load_lds_dwordx4 v[230:231], off
	s_waitcnt vmcnt(8)
	s_waitcnt lgkmcnt(0)
	s_barrier
	s_waitcnt lgkmcnt(0)
	v_mfma_f32_16x16x32_bf16 v[124:127], v[156:159], v[188:191], v[124:127]
	v_mfma_f32_16x16x32_bf16 v[120:123], v[164:167], v[188:191], v[120:123]
	v_mfma_f32_16x16x32_bf16 v[116:119], v[156:159], v[196:199], v[116:119]
	v_mfma_f32_16x16x32_bf16 v[112:115], v[164:167], v[196:199], v[112:115]
	v_mfma_f32_16x16x32_bf16 v[108:111], v[156:159], v[204:207], v[108:111]
	v_mfma_f32_16x16x32_bf16 v[104:107], v[164:167], v[204:207], v[104:107]
	v_mfma_f32_16x16x32_bf16 v[100:103], v[156:159], v[216:219], v[100:103]
	v_mfma_f32_16x16x32_bf16 v[96:99], v[164:167], v[216:219], v[96:99]
	v_mfma_f32_16x16x32_bf16 v[124:127], v[160:163], v[192:195], v[124:127]
	v_mfma_f32_16x16x32_bf16 v[120:123], v[168:171], v[192:195], v[120:123]
	v_mfma_f32_16x16x32_bf16 v[116:119], v[160:163], v[200:203], v[116:119]
	v_mfma_f32_16x16x32_bf16 v[112:115], v[168:171], v[200:203], v[112:115]
	v_mfma_f32_16x16x32_bf16 v[108:111], v[160:163], v[212:215], v[108:111]
	v_mfma_f32_16x16x32_bf16 v[104:107], v[168:171], v[212:215], v[104:107]
	v_mfma_f32_16x16x32_bf16 v[100:103], v[160:163], v[220:223], v[100:103]
	v_mfma_f32_16x16x32_bf16 v[96:99], v[168:171], v[220:223], v[96:99]
	v_mfma_f32_16x16x32_bf16 v[68:71], v[172:175], v[188:191], v[68:71]
	v_mfma_f32_16x16x32_bf16 v[60:63], v[180:183], v[188:191], v[60:63]
	v_mfma_f32_16x16x32_bf16 v[52:55], v[172:175], v[196:199], v[52:55]
	v_mfma_f32_16x16x32_bf16 v[48:51], v[180:183], v[196:199], v[48:51]
	v_mfma_f32_16x16x32_bf16 v[44:47], v[172:175], v[204:207], v[44:47]
	v_mfma_f32_16x16x32_bf16 v[40:43], v[180:183], v[204:207], v[40:43]
	v_mfma_f32_16x16x32_bf16 v[36:39], v[172:175], v[216:219], v[36:39]
	v_mfma_f32_16x16x32_bf16 v[32:35], v[180:183], v[216:219], v[32:35]
	v_mfma_f32_16x16x32_bf16 v[68:71], v[176:179], v[192:195], v[68:71]
	v_mfma_f32_16x16x32_bf16 v[60:63], v[184:187], v[192:195], v[60:63]
	v_mfma_f32_16x16x32_bf16 v[52:55], v[176:179], v[200:203], v[52:55]
	v_mfma_f32_16x16x32_bf16 v[48:51], v[184:187], v[200:203], v[48:51]
	v_mfma_f32_16x16x32_bf16 v[44:47], v[176:179], v[212:215], v[44:47]
	v_mfma_f32_16x16x32_bf16 v[40:43], v[184:187], v[212:215], v[40:43]
	v_mfma_f32_16x16x32_bf16 v[36:39], v[176:179], v[220:223], v[36:39]
	v_mfma_f32_16x16x32_bf16 v[32:35], v[184:187], v[220:223], v[32:35]
	s_barrier
	s_add_i32 s24, s26, s61
	v_lshl_add_u64 v[208:209], v[208:209], 0, s[38:39]
	s_mov_b32 m0, s24
	ds_read_b128 v[188:191], v155 offset:49152
	ds_read_b128 v[192:195], v155 offset:50176
	ds_read_b128 v[196:199], v155 offset:51200
	ds_read_b128 v[200:203], v155 offset:52224
	ds_read_b128 v[204:207], v155 offset:53248
	ds_read_b128 v[212:215], v155 offset:54272
	ds_read_b128 v[216:219], v155 offset:55296
	ds_read_b128 v[220:223], v155 offset:56320
	global_load_lds_dwordx4 v[208:209], off
	s_add_i32 m0, s24, 0x2000
	s_add_u32 s14, s14, 0x80080
	v_lshl_add_u64 v[208:209], v[224:225], 0, s[38:39]
	s_addc_u32 s15, s15, 0
	s_add_i32 s24, s27, s61
	global_load_lds_dwordx4 v[208:209], off
	v_lshl_add_u64 v[208:209], s[14:15], 0, v[130:131]
	s_mov_b32 m0, s24
	s_nop 0
	global_load_lds_dwordx4 v[208:209], off
	v_lshl_add_u64 v[208:209], s[14:15], 0, v[134:135]
	s_add_i32 m0, s24, 0x2000
	s_nop 0
	global_load_lds_dwordx4 v[208:209], off
	v_lshl_add_u64 v[208:209], v[226:227], 0, s[38:39]
	s_mov_b32 m0, s69
	s_nop 0
	global_load_lds_dwordx4 v[208:209], off
	v_lshl_add_u64 v[208:209], v[228:229], 0, s[38:39]
	s_mov_b32 m0, s76
	s_nop 0
	global_load_lds_dwordx4 v[208:209], off
	s_waitcnt vmcnt(8)
	s_waitcnt lgkmcnt(0)
	s_barrier
	s_waitcnt lgkmcnt(0)
	v_mfma_f32_16x16x32_bf16 v[92:95], v[156:159], v[188:191], v[92:95]
	v_mfma_f32_16x16x32_bf16 v[88:91], v[164:167], v[188:191], v[88:91]
	v_mfma_f32_16x16x32_bf16 v[84:87], v[156:159], v[196:199], v[84:87]
	v_mfma_f32_16x16x32_bf16 v[80:83], v[164:167], v[196:199], v[80:83]
	v_mfma_f32_16x16x32_bf16 v[76:79], v[156:159], v[204:207], v[76:79]
	v_mfma_f32_16x16x32_bf16 v[72:75], v[164:167], v[204:207], v[72:75]
	v_mfma_f32_16x16x32_bf16 v[64:67], v[156:159], v[216:219], v[64:67]
	v_mfma_f32_16x16x32_bf16 v[56:59], v[164:167], v[216:219], v[56:59]
	v_mfma_f32_16x16x32_bf16 v[92:95], v[160:163], v[192:195], v[92:95]
	v_mfma_f32_16x16x32_bf16 v[88:91], v[168:171], v[192:195], v[88:91]
	v_mfma_f32_16x16x32_bf16 v[84:87], v[160:163], v[200:203], v[84:87]
	v_mfma_f32_16x16x32_bf16 v[80:83], v[168:171], v[200:203], v[80:83]
	v_mfma_f32_16x16x32_bf16 v[76:79], v[160:163], v[212:215], v[76:79]
	v_mfma_f32_16x16x32_bf16 v[72:75], v[168:171], v[212:215], v[72:75]
	v_mfma_f32_16x16x32_bf16 v[64:67], v[160:163], v[220:223], v[64:67]
	v_mfma_f32_16x16x32_bf16 v[56:59], v[168:171], v[220:223], v[56:59]
	v_mfma_f32_16x16x32_bf16 v[28:31], v[172:175], v[188:191], v[28:31]
	v_mfma_f32_16x16x32_bf16 v[24:27], v[180:183], v[188:191], v[24:27]
	v_mfma_f32_16x16x32_bf16 v[20:23], v[172:175], v[196:199], v[20:23]
	v_mfma_f32_16x16x32_bf16 v[16:19], v[180:183], v[196:199], v[16:19]
	v_mfma_f32_16x16x32_bf16 v[12:15], v[172:175], v[204:207], v[12:15]
	v_mfma_f32_16x16x32_bf16 v[8:11], v[180:183], v[204:207], v[8:11]
	v_mfma_f32_16x16x32_bf16 v[4:7], v[172:175], v[216:219], v[4:7]
	v_mfma_f32_16x16x32_bf16 v[0:3], v[180:183], v[216:219], v[0:3]
	v_mfma_f32_16x16x32_bf16 v[28:31], v[176:179], v[192:195], v[28:31]
	v_mfma_f32_16x16x32_bf16 v[24:27], v[184:187], v[192:195], v[24:27]
	v_mfma_f32_16x16x32_bf16 v[20:23], v[176:179], v[200:203], v[20:23]
	v_mfma_f32_16x16x32_bf16 v[16:19], v[184:187], v[200:203], v[16:19]
	v_mfma_f32_16x16x32_bf16 v[12:15], v[176:179], v[212:215], v[12:15]
	v_mfma_f32_16x16x32_bf16 v[8:11], v[184:187], v[212:215], v[8:11]
	v_mfma_f32_16x16x32_bf16 v[4:7], v[176:179], v[220:223], v[4:7]
	v_mfma_f32_16x16x32_bf16 v[0:3], v[184:187], v[220:223], v[0:3]
	s_barrier
	s_add_i32 s87, s87, 2
	s_add_u32 s12, s12, 0x100
	s_addc_u32 s13, s13, 0
	s_add_u32 s85, s85, 0x100
	s_addc_u32 s86, s86, 0
	s_cmp_gt_u32 s87, 29
	s_cbranch_scc0 .LBB0_447
	s_and_b64 vcc, exec, s[40:41]
	s_cbranch_vccz .LBB0_450
	s_barrier

.LBB0_521:
	s_or_b64 exec, exec, s[0:1]
	s_setprio 0
	s_cmpk_lt_i32 s2, 0x100
	s_cselect_b64 s[4:5], -1, 0
	s_add_u32 s35, s92, 0x10d00000
	s_addc_u32 s26, s93, 0
	s_add_u32 s13, s92, 0x9700000
	s_addc_u32 s33, s93, 0
	s_cmpk_gt_i32 s2, 0xff
	s_movk_i32 s69, 0x100
	s_waitcnt lgkmcnt(0)
	s_barrier
	v_writelane_b32 v233, s26, 21
	s_cbranch_scc1 .LBB0_523
	s_lshl_b32 s0, s2, 5
	s_and_b32 s0, s0, 0xe0
	s_ashr_i32 s12, s2, 3
	s_add_i32 s0, s0, s12
	s_ashr_i32 s0, s0, 5
	s_ashr_i32 s1, s0, 31
	s_lshl_b64 s[14:15], s[0:1], 23
	s_add_u32 s1, s92, s14
	s_addc_u32 s14, s93, s15
	s_lshl_b32 s12, s12, 8
	s_and_b32 s12, s12, 0x700
	s_lshl_b32 s15, s12, 12
	s_add_u32 s1, s1, s15
	s_addc_u32 s14, s14, 0
	s_bfe_u32 s15, s2, 0x20006
	s_lshl_b32 s24, s15, 8
	s_add_u32 s1, s1, s24
	s_addc_u32 s14, s14, 0
	s_add_u32 s60, s1, 0xcd00c00
	s_addc_u32 s61, s14, 0
	s_add_u32 s58, s1, 0x17d00c00
	s_addc_u32 s59, s14, 0
	s_lshl_b32 s0, s0, 2
	s_or_b32 s0, s0, s15
	s_ashr_i32 s1, s0, 31
	s_lshl_b64 s[24:25], s[0:1], 16
	s_add_u32 s14, s13, s24
	s_addc_u32 s15, s33, s25
	s_add_u32 s42, s46, s24
	s_addc_u32 s43, s47, s25
	s_lshl_b64 s[0:1], s[0:1], 19
	s_add_u32 s0, s35, s0
	s_addc_u32 s1, s26, s1
	s_lshl_b32 s12, s12, 8
	s_add_u32 s0, s0, s12
	s_addc_u32 s1, s1, 0
	s_branch .LBB0_524

.Lgprio_skip2:
	s_bitcmp1_b32 s2, 0
	s_cbranch_scc0 .Ldf_skip_p4
	v_writelane_b32 v234, s0, 0
	v_writelane_b32 v234, s1, 1
	v_writelane_b32 v234, s2, 2
	v_writelane_b32 v234, s3, 3
	v_writelane_b32 v234, s4, 4
	v_writelane_b32 v234, s5, 5
	v_writelane_b32 v234, s6, 6
	v_writelane_b32 v234, s7, 7
	v_writelane_b32 v234, s8, 8
	v_writelane_b32 v234, s9, 9
	v_writelane_b32 v234, s10, 10
	v_writelane_b32 v234, s11, 11
	v_writelane_b32 v234, s12, 12
	v_writelane_b32 v234, s13, 13
	v_writelane_b32 v234, s14, 14
	v_writelane_b32 v234, s15, 15
	v_writelane_b32 v234, s16, 16
	v_writelane_b32 v234, s17, 17
	v_writelane_b32 v234, s18, 18
	v_writelane_b32 v234, s19, 19
	v_writelane_b32 v234, s20, 20
	v_writelane_b32 v234, s21, 21
	v_writelane_b32 v234, s22, 22
	v_writelane_b32 v234, s23, 23
	v_writelane_b32 v234, s24, 24
	v_writelane_b32 v234, s25, 25
	v_writelane_b32 v234, s26, 26
	v_writelane_b32 v234, s27, 27
	v_writelane_b32 v234, s28, 28
	v_writelane_b32 v234, s29, 29
	v_writelane_b32 v234, s30, 30
	v_writelane_b32 v234, s31, 31
	v_writelane_b32 v234, s32, 32
	v_writelane_b32 v234, s33, 33
	v_writelane_b32 v234, s34, 34
	v_writelane_b32 v234, s35, 35
	v_writelane_b32 v234, s36, 36
	v_writelane_b32 v234, s37, 37
	v_writelane_b32 v234, s38, 38
	v_writelane_b32 v234, s39, 39
	v_writelane_b32 v234, s40, 40
	v_writelane_b32 v234, s41, 41
	v_writelane_b32 v234, s42, 42
	v_writelane_b32 v234, s43, 43
	v_writelane_b32 v234, s44, 44
	v_writelane_b32 v234, s45, 45
	v_writelane_b32 v234, s46, 46
	v_writelane_b32 v234, s47, 47
	v_writelane_b32 v234, s48, 48
	v_writelane_b32 v234, s49, 49
	v_writelane_b32 v234, s50, 50
	v_writelane_b32 v234, s51, 51
	v_writelane_b32 v234, s52, 52
	v_writelane_b32 v234, s53, 53
	v_writelane_b32 v234, s54, 54
	v_writelane_b32 v234, s55, 55
	v_writelane_b32 v234, s56, 56
	v_writelane_b32 v234, s57, 57
	v_writelane_b32 v234, s58, 58
	v_writelane_b32 v234, s59, 59
	v_writelane_b32 v234, s60, 60
	v_writelane_b32 v234, s61, 61
	v_writelane_b32 v234, s62, 62
	v_writelane_b32 v234, s63, 63
	v_writelane_b32 v235, s64, 0
	v_writelane_b32 v235, s65, 1
	v_writelane_b32 v235, s66, 2
	v_writelane_b32 v235, s67, 3
	v_writelane_b32 v235, s68, 4
	v_writelane_b32 v235, s69, 5
	v_writelane_b32 v235, s70, 6
	v_writelane_b32 v235, s71, 7
	v_writelane_b32 v235, s72, 8
	v_writelane_b32 v235, s73, 9
	v_writelane_b32 v235, s74, 10
	v_writelane_b32 v235, s75, 11
	v_writelane_b32 v235, s76, 12
	v_writelane_b32 v235, s77, 13
	v_writelane_b32 v235, s78, 14
	v_writelane_b32 v235, s79, 15
	v_writelane_b32 v235, s80, 16
	v_writelane_b32 v235, s81, 17
	v_writelane_b32 v235, s82, 18
	v_writelane_b32 v235, s83, 19
	v_writelane_b32 v235, s84, 20
	v_writelane_b32 v235, s85, 21
	v_writelane_b32 v235, s86, 22
	v_writelane_b32 v235, s87, 23
	v_writelane_b32 v235, s88, 24
	v_writelane_b32 v235, s89, 25
	v_writelane_b32 v235, s90, 26
	v_writelane_b32 v235, s91, 27
	v_writelane_b32 v235, s92, 28
	v_writelane_b32 v235, s93, 29
	v_writelane_b32 v235, s94, 30
	v_writelane_b32 v235, s95, 31
	v_writelane_b32 v235, s96, 32
	v_writelane_b32 v235, s97, 33
	v_writelane_b32 v235, vcc_lo, 34
	v_writelane_b32 v235, vcc_hi, 35
	v_readlane_b32 s70, v233, 45
	v_readlane_b32 s71, v233, 46
	s_add_u32 s22, s92, 0x4500000
	s_addc_u32 s23, s93, 0
	s_add_u32 s40, s92, 0x1400000
	s_addc_u32 s41, s93, 0
	v_mov_b32_e32 v0, v210
	s_nop 0
	v_readfirstlane_b32 s1, v0
	s_nop 3
	s_ashr_i32 s13, s1, 6
	s_lshr_b32 s0, s2, 1
	s_lshl_b32 s0, s0, 3
	s_add_i32 s33, s13, s0
	s_addk_i32 s33, 0x1000
	s_movk_i32 s12, 0x80
	s_movk_i32 s101, 0x1c00
	s_mov_b32 s100, 4
	s_branch .Lp3t_setup

.LBB0_642:
	ds_read_b128 v[144:147], v151
	ds_read_b128 v[154:157], v151 offset:1024
	ds_read_b128 v[158:161], v151 offset:2048
	ds_read_b128 v[162:165], v151 offset:3072
	ds_read_b128 v[166:169], v152
	ds_read_b128 v[170:173], v152 offset:1024
	ds_read_b128 v[174:177], v152 offset:2048
	ds_read_b128 v[178:181], v152 offset:3072
	s_add_u32 s24, s58, 0xfff80080
	s_addc_u32 s25, s59, -1
	s_cmp_eq_u32 s85, 28
	s_cselect_b32 s63, s15, s25
	s_cselect_b32 s62, s51, s24
	s_cselect_b32 s61, s49, s84
	s_cselect_b32 s60, s82, s83
	v_lshl_add_u64 v[216:217], s[58:59], 0, v[136:137]
	s_add_i32 m0, s57, 0xc000
	ds_read_b128 v[182:185], v153
	ds_read_b128 v[186:189], v153 offset:1024
	ds_read_b128 v[190:193], v153 offset:2048
	ds_read_b128 v[194:197], v153 offset:3072
	ds_read_b128 v[198:201], v153 offset:4096
	ds_read_b128 v[202:205], v153 offset:5120
	ds_read_b128 v[206:209], v153 offset:6144
	ds_read_b128 v[212:215], v153 offset:7168
	global_load_lds_dwordx4 v[216:217], off
	v_lshl_add_u64 v[216:217], s[58:59], 0, v[138:139]
	s_add_i32 m0, s57, 0xe000
	s_nop 0
	global_load_lds_dwordx4 v[216:217], off
	s_waitcnt vmcnt(8)
	s_waitcnt lgkmcnt(0)
	s_barrier
	s_waitcnt lgkmcnt(0)
	v_mfma_f32_16x16x32_bf16 v[124:127], v[144:147], v[182:185], v[124:127]
	v_mfma_f32_16x16x32_bf16 v[120:123], v[158:161], v[182:185], v[120:123]
	v_mfma_f32_16x16x32_bf16 v[108:111], v[144:147], v[190:193], v[108:111]
	v_mfma_f32_16x16x32_bf16 v[104:107], v[158:161], v[190:193], v[104:107]
	v_mfma_f32_16x16x32_bf16 v[92:95], v[144:147], v[198:201], v[92:95]
	v_mfma_f32_16x16x32_bf16 v[88:91], v[158:161], v[198:201], v[88:91]
	v_mfma_f32_16x16x32_bf16 v[76:79], v[144:147], v[206:209], v[76:79]
	v_mfma_f32_16x16x32_bf16 v[72:75], v[158:161], v[206:209], v[72:75]
	v_mfma_f32_16x16x32_bf16 v[124:127], v[154:157], v[186:189], v[124:127]
	v_mfma_f32_16x16x32_bf16 v[120:123], v[162:165], v[186:189], v[120:123]
	v_mfma_f32_16x16x32_bf16 v[108:111], v[154:157], v[194:197], v[108:111]
	v_mfma_f32_16x16x32_bf16 v[104:107], v[162:165], v[194:197], v[104:107]
	v_mfma_f32_16x16x32_bf16 v[92:95], v[154:157], v[202:205], v[92:95]
	v_mfma_f32_16x16x32_bf16 v[88:91], v[162:165], v[202:205], v[88:91]
	v_mfma_f32_16x16x32_bf16 v[76:79], v[154:157], v[212:215], v[76:79]
	v_mfma_f32_16x16x32_bf16 v[72:75], v[162:165], v[212:215], v[72:75]
	v_mfma_f32_16x16x32_bf16 v[116:119], v[166:169], v[182:185], v[116:119]
	v_mfma_f32_16x16x32_bf16 v[112:115], v[174:177], v[182:185], v[112:115]
	v_mfma_f32_16x16x32_bf16 v[100:103], v[166:169], v[190:193], v[100:103]
	v_mfma_f32_16x16x32_bf16 v[96:99], v[174:177], v[190:193], v[96:99]
	v_mfma_f32_16x16x32_bf16 v[84:87], v[166:169], v[198:201], v[84:87]
	v_mfma_f32_16x16x32_bf16 v[80:83], v[174:177], v[198:201], v[80:83]
	v_mfma_f32_16x16x32_bf16 v[68:71], v[166:169], v[206:209], v[68:71]
	v_mfma_f32_16x16x32_bf16 v[64:67], v[174:177], v[206:209], v[64:67]
	v_mfma_f32_16x16x32_bf16 v[116:119], v[170:173], v[186:189], v[116:119]
	v_mfma_f32_16x16x32_bf16 v[112:115], v[178:181], v[186:189], v[112:115]
	v_mfma_f32_16x16x32_bf16 v[100:103], v[170:173], v[194:197], v[100:103]
	v_mfma_f32_16x16x32_bf16 v[96:99], v[178:181], v[194:197], v[96:99]
	v_mfma_f32_16x16x32_bf16 v[84:87], v[170:173], v[202:205], v[84:87]
	v_mfma_f32_16x16x32_bf16 v[80:83], v[178:181], v[202:205], v[80:83]
	v_mfma_f32_16x16x32_bf16 v[68:71], v[170:173], v[212:215], v[68:71]
	v_mfma_f32_16x16x32_bf16 v[64:67], v[178:181], v[212:215], v[64:67]
	s_barrier
	s_add_i32 s24, s80, s65
	v_lshl_add_u64 v[216:217], s[60:61], 0, v[130:131]
	s_mov_b32 m0, s24
	ds_read_b128 v[182:185], v153 offset:16384
	ds_read_b128 v[186:189], v153 offset:17408
	ds_read_b128 v[190:193], v153 offset:18432
	ds_read_b128 v[194:197], v153 offset:19456
	ds_read_b128 v[198:201], v153 offset:20480
	ds_read_b128 v[202:205], v153 offset:21504
	ds_read_b128 v[206:209], v153 offset:22528
	ds_read_b128 v[212:215], v153 offset:23552
	global_load_lds_dwordx4 v[216:217], off
	s_add_i32 m0, s24, 0x2000
	s_add_u32 s24, s60, 0x80000
	v_lshl_add_u64 v[218:219], s[60:61], 0, v[134:135]
	s_addc_u32 s25, s61, 0
	s_add_i32 s26, s81, s65
	global_load_lds_dwordx4 v[218:219], off
	v_lshl_add_u64 v[220:221], s[24:25], 0, v[130:131]
	s_mov_b32 m0, s26
	v_lshl_add_u64 v[222:223], s[62:63], 0, v[132:133]
	global_load_lds_dwordx4 v[220:221], off
	v_lshl_add_u64 v[220:221], s[24:25], 0, v[134:135]
	s_add_i32 m0, s26, 0x2000
	s_nop 0
	global_load_lds_dwordx4 v[220:221], off
	v_lshl_add_u64 v[220:221], s[62:63], 0, v[128:129]
	s_mov_b32 m0, s57
	s_nop 0
	global_load_lds_dwordx4 v[220:221], off
	s_mov_b32 m0, s66
	s_nop 0
	global_load_lds_dwordx4 v[222:223], off
	s_waitcnt vmcnt(8)
	s_waitcnt lgkmcnt(0)
	s_barrier
	s_waitcnt lgkmcnt(0)
	v_mfma_f32_16x16x32_bf16 v[60:63], v[144:147], v[182:185], v[60:63]
	v_mfma_f32_16x16x32_bf16 v[56:59], v[158:161], v[182:185], v[56:59]
	v_mfma_f32_16x16x32_bf16 v[44:47], v[144:147], v[190:193], v[44:47]
	v_mfma_f32_16x16x32_bf16 v[40:43], v[158:161], v[190:193], v[40:43]
	v_mfma_f32_16x16x32_bf16 v[28:31], v[144:147], v[198:201], v[28:31]
	v_mfma_f32_16x16x32_bf16 v[24:27], v[158:161], v[198:201], v[24:27]
	v_mfma_f32_16x16x32_bf16 v[12:15], v[144:147], v[206:209], v[12:15]
	v_mfma_f32_16x16x32_bf16 v[8:11], v[158:161], v[206:209], v[8:11]
	v_mfma_f32_16x16x32_bf16 v[60:63], v[154:157], v[186:189], v[60:63]
	v_mfma_f32_16x16x32_bf16 v[56:59], v[162:165], v[186:189], v[56:59]
	v_mfma_f32_16x16x32_bf16 v[44:47], v[154:157], v[194:197], v[44:47]
	v_mfma_f32_16x16x32_bf16 v[40:43], v[162:165], v[194:197], v[40:43]
	v_mfma_f32_16x16x32_bf16 v[28:31], v[154:157], v[202:205], v[28:31]
	v_mfma_f32_16x16x32_bf16 v[24:27], v[162:165], v[202:205], v[24:27]
	v_mfma_f32_16x16x32_bf16 v[12:15], v[154:157], v[212:215], v[12:15]
	v_mfma_f32_16x16x32_bf16 v[8:11], v[162:165], v[212:215], v[8:11]
	v_mfma_f32_16x16x32_bf16 v[52:55], v[166:169], v[182:185], v[52:55]
	v_mfma_f32_16x16x32_bf16 v[48:51], v[174:177], v[182:185], v[48:51]
	v_mfma_f32_16x16x32_bf16 v[36:39], v[166:169], v[190:193], v[36:39]
	v_mfma_f32_16x16x32_bf16 v[32:35], v[174:177], v[190:193], v[32:35]
	v_mfma_f32_16x16x32_bf16 v[20:23], v[166:169], v[198:201], v[20:23]
	v_mfma_f32_16x16x32_bf16 v[16:19], v[174:177], v[198:201], v[16:19]
	v_mfma_f32_16x16x32_bf16 v[4:7], v[166:169], v[206:209], v[4:7]
	v_mfma_f32_16x16x32_bf16 v[0:3], v[174:177], v[206:209], v[0:3]
	v_mfma_f32_16x16x32_bf16 v[52:55], v[170:173], v[186:189], v[52:55]
	v_mfma_f32_16x16x32_bf16 v[48:51], v[178:181], v[186:189], v[48:51]
	v_mfma_f32_16x16x32_bf16 v[36:39], v[170:173], v[194:197], v[36:39]
	v_mfma_f32_16x16x32_bf16 v[32:35], v[178:181], v[194:197], v[32:35]
	v_mfma_f32_16x16x32_bf16 v[20:23], v[170:173], v[202:205], v[20:23]
	v_mfma_f32_16x16x32_bf16 v[16:19], v[178:181], v[202:205], v[16:19]
	v_mfma_f32_16x16x32_bf16 v[4:7], v[170:173], v[212:215], v[4:7]
	v_mfma_f32_16x16x32_bf16 v[0:3], v[178:181], v[212:215], v[0:3]
	s_barrier
	s_add_i32 s26, 0, 0x18000
	s_add_i32 s27, 0, 0x1c000
	v_add_u32_e32 v162, s26, v149
	v_add_u32_e32 v178, s27, v149
	ds_read_b128 v[144:147], v162
	ds_read_b128 v[154:157], v162 offset:1024
	ds_read_b128 v[158:161], v162 offset:2048
	ds_read_b128 v[162:165], v162 offset:3072
	ds_read_b128 v[166:169], v178
	ds_read_b128 v[170:173], v178 offset:1024
	ds_read_b128 v[174:177], v178 offset:2048
	ds_read_b128 v[178:181], v178 offset:3072
	s_add_u32 s24, s62, 0x80000
	s_addc_u32 s25, s63, 0
	s_mov_b32 m0, s67
	v_lshl_add_u64 v[224:225], s[24:25], 0, v[128:129]
	ds_read_b128 v[182:185], v153 offset:32768
	ds_read_b128 v[186:189], v153 offset:33792
	ds_read_b128 v[190:193], v153 offset:34816
	ds_read_b128 v[194:197], v153 offset:35840
	ds_read_b128 v[198:201], v153 offset:36864
	ds_read_b128 v[202:205], v153 offset:37888
	ds_read_b128 v[206:209], v153 offset:38912
	ds_read_b128 v[212:215], v153 offset:39936
	global_load_lds_dwordx4 v[224:225], off
	v_lshl_add_u64 v[224:225], s[24:25], 0, v[132:133]
	s_mov_b32 m0, s68
	s_nop 0
	global_load_lds_dwordx4 v[224:225], off
	s_waitcnt vmcnt(8)
	s_waitcnt lgkmcnt(0)
	s_barrier
	s_waitcnt lgkmcnt(0)
	v_mfma_f32_16x16x32_bf16 v[124:127], v[144:147], v[182:185], v[124:127]
	v_mfma_f32_16x16x32_bf16 v[120:123], v[158:161], v[182:185], v[120:123]
	v_mfma_f32_16x16x32_bf16 v[108:111], v[144:147], v[190:193], v[108:111]
	v_mfma_f32_16x16x32_bf16 v[104:107], v[158:161], v[190:193], v[104:107]
	v_mfma_f32_16x16x32_bf16 v[92:95], v[144:147], v[198:201], v[92:95]
	v_mfma_f32_16x16x32_bf16 v[88:91], v[158:161], v[198:201], v[88:91]
	v_mfma_f32_16x16x32_bf16 v[76:79], v[144:147], v[206:209], v[76:79]
	v_mfma_f32_16x16x32_bf16 v[72:75], v[158:161], v[206:209], v[72:75]
	v_mfma_f32_16x16x32_bf16 v[124:127], v[154:157], v[186:189], v[124:127]
	v_mfma_f32_16x16x32_bf16 v[120:123], v[162:165], v[186:189], v[120:123]
	v_mfma_f32_16x16x32_bf16 v[108:111], v[154:157], v[194:197], v[108:111]
	v_mfma_f32_16x16x32_bf16 v[104:107], v[162:165], v[194:197], v[104:107]
	v_mfma_f32_16x16x32_bf16 v[92:95], v[154:157], v[202:205], v[92:95]
	v_mfma_f32_16x16x32_bf16 v[88:91], v[162:165], v[202:205], v[88:91]
	v_mfma_f32_16x16x32_bf16 v[76:79], v[154:157], v[212:215], v[76:79]
	v_mfma_f32_16x16x32_bf16 v[72:75], v[162:165], v[212:215], v[72:75]
	v_mfma_f32_16x16x32_bf16 v[116:119], v[166:169], v[182:185], v[116:119]
	v_mfma_f32_16x16x32_bf16 v[112:115], v[174:177], v[182:185], v[112:115]
	v_mfma_f32_16x16x32_bf16 v[100:103], v[166:169], v[190:193], v[100:103]
	v_mfma_f32_16x16x32_bf16 v[96:99], v[174:177], v[190:193], v[96:99]
	v_mfma_f32_16x16x32_bf16 v[84:87], v[166:169], v[198:201], v[84:87]
	v_mfma_f32_16x16x32_bf16 v[80:83], v[174:177], v[198:201], v[80:83]
	v_mfma_f32_16x16x32_bf16 v[68:71], v[166:169], v[206:209], v[68:71]
	v_mfma_f32_16x16x32_bf16 v[64:67], v[174:177], v[206:209], v[64:67]
	v_mfma_f32_16x16x32_bf16 v[116:119], v[170:173], v[186:189], v[116:119]
	v_mfma_f32_16x16x32_bf16 v[112:115], v[178:181], v[186:189], v[112:115]
	v_mfma_f32_16x16x32_bf16 v[100:103], v[170:173], v[194:197], v[100:103]
	v_mfma_f32_16x16x32_bf16 v[96:99], v[178:181], v[194:197], v[96:99]
	v_mfma_f32_16x16x32_bf16 v[84:87], v[170:173], v[202:205], v[84:87]
	v_mfma_f32_16x16x32_bf16 v[80:83], v[178:181], v[202:205], v[80:83]
	v_mfma_f32_16x16x32_bf16 v[68:71], v[170:173], v[212:215], v[68:71]
	v_mfma_f32_16x16x32_bf16 v[64:67], v[178:181], v[212:215], v[64:67]
	s_barrier
	s_add_i32 s24, s26, s65
	v_lshl_add_u64 v[216:217], v[216:217], 0, s[4:5]
	s_mov_b32 m0, s24
	ds_read_b128 v[182:185], v153 offset:49152
	ds_read_b128 v[186:189], v153 offset:50176
	ds_read_b128 v[190:193], v153 offset:51200
	ds_read_b128 v[194:197], v153 offset:52224
	ds_read_b128 v[198:201], v153 offset:53248
	ds_read_b128 v[202:205], v153 offset:54272
	ds_read_b128 v[206:209], v153 offset:55296
	ds_read_b128 v[212:215], v153 offset:56320
	global_load_lds_dwordx4 v[216:217], off
	s_add_i32 m0, s24, 0x2000
	s_add_u32 s24, s60, 0x80080
	v_lshl_add_u64 v[216:217], v[218:219], 0, s[4:5]
	s_addc_u32 s25, s61, 0
	s_add_i32 s26, s27, s65
	global_load_lds_dwordx4 v[216:217], off
	v_lshl_add_u64 v[216:217], s[24:25], 0, v[130:131]
	s_mov_b32 m0, s26
	s_nop 0
	global_load_lds_dwordx4 v[216:217], off
	v_lshl_add_u64 v[216:217], s[24:25], 0, v[134:135]
	s_add_i32 m0, s26, 0x2000
	s_nop 0
	global_load_lds_dwordx4 v[216:217], off
	v_lshl_add_u64 v[216:217], v[220:221], 0, s[4:5]
	s_mov_b32 m0, s76
	s_nop 0
	global_load_lds_dwordx4 v[216:217], off
	v_lshl_add_u64 v[216:217], v[222:223], 0, s[4:5]
	s_mov_b32 m0, s77
	s_nop 0
	global_load_lds_dwordx4 v[216:217], off
	s_waitcnt vmcnt(8)
	s_waitcnt lgkmcnt(0)
	s_barrier
	s_waitcnt lgkmcnt(0)
	v_mfma_f32_16x16x32_bf16 v[60:63], v[144:147], v[182:185], v[60:63]
	v_mfma_f32_16x16x32_bf16 v[56:59], v[158:161], v[182:185], v[56:59]
	v_mfma_f32_16x16x32_bf16 v[44:47], v[144:147], v[190:193], v[44:47]
	v_mfma_f32_16x16x32_bf16 v[40:43], v[158:161], v[190:193], v[40:43]
	v_mfma_f32_16x16x32_bf16 v[28:31], v[144:147], v[198:201], v[28:31]
	v_mfma_f32_16x16x32_bf16 v[24:27], v[158:161], v[198:201], v[24:27]
	v_mfma_f32_16x16x32_bf16 v[12:15], v[144:147], v[206:209], v[12:15]
	v_mfma_f32_16x16x32_bf16 v[8:11], v[158:161], v[206:209], v[8:11]
	v_mfma_f32_16x16x32_bf16 v[60:63], v[154:157], v[186:189], v[60:63]
	v_mfma_f32_16x16x32_bf16 v[56:59], v[162:165], v[186:189], v[56:59]
	v_mfma_f32_16x16x32_bf16 v[44:47], v[154:157], v[194:197], v[44:47]
	v_mfma_f32_16x16x32_bf16 v[40:43], v[162:165], v[194:197], v[40:43]
	v_mfma_f32_16x16x32_bf16 v[28:31], v[154:157], v[202:205], v[28:31]
	v_mfma_f32_16x16x32_bf16 v[24:27], v[162:165], v[202:205], v[24:27]
	v_mfma_f32_16x16x32_bf16 v[12:15], v[154:157], v[212:215], v[12:15]
	v_mfma_f32_16x16x32_bf16 v[8:11], v[162:165], v[212:215], v[8:11]
	v_mfma_f32_16x16x32_bf16 v[52:55], v[166:169], v[182:185], v[52:55]
	v_mfma_f32_16x16x32_bf16 v[48:51], v[174:177], v[182:185], v[48:51]
	v_mfma_f32_16x16x32_bf16 v[36:39], v[166:169], v[190:193], v[36:39]
	v_mfma_f32_16x16x32_bf16 v[32:35], v[174:177], v[190:193], v[32:35]
	v_mfma_f32_16x16x32_bf16 v[20:23], v[166:169], v[198:201], v[20:23]
	v_mfma_f32_16x16x32_bf16 v[16:19], v[174:177], v[198:201], v[16:19]
	v_mfma_f32_16x16x32_bf16 v[4:7], v[166:169], v[206:209], v[4:7]
	v_mfma_f32_16x16x32_bf16 v[0:3], v[174:177], v[206:209], v[0:3]
	v_mfma_f32_16x16x32_bf16 v[52:55], v[170:173], v[186:189], v[52:55]
	v_mfma_f32_16x16x32_bf16 v[48:51], v[178:181], v[186:189], v[48:51]
	v_mfma_f32_16x16x32_bf16 v[36:39], v[170:173], v[194:197], v[36:39]
	v_mfma_f32_16x16x32_bf16 v[32:35], v[178:181], v[194:197], v[32:35]
	v_mfma_f32_16x16x32_bf16 v[20:23], v[170:173], v[202:205], v[20:23]
	v_mfma_f32_16x16x32_bf16 v[16:19], v[178:181], v[202:205], v[16:19]
	v_mfma_f32_16x16x32_bf16 v[4:7], v[170:173], v[212:215], v[4:7]
	v_mfma_f32_16x16x32_bf16 v[0:3], v[178:181], v[212:215], v[0:3]
	s_barrier
	s_add_i32 s85, s85, 2
	s_add_u32 s58, s58, 0x100
	s_addc_u32 s59, s59, 0
	s_add_u32 s83, s83, 0x100
	s_addc_u32 s84, s84, 0
	s_cmp_gt_u32 s85, 29
	s_cbranch_scc0 .LBB0_642
	s_and_b64 vcc, exec, s[46:47]
	s_cbranch_vccz .LBB0_645
	s_barrier

.LBB0_717:
	s_or_b64 exec, exec, s[0:1]
	s_setprio 0
	s_waitcnt lgkmcnt(0)
	v_mov_b32_e32 v0, v210
	s_movk_i32 s0, 0x1800
	s_barrier
	s_nop 0
	v_readfirstlane_b32 s14, v0
	v_cmp_gt_i32_e32 vcc, s0, v0
	s_and_saveexec_b64 s[0:1], vcc
	s_cbranch_execz .LBB0_720
	v_ashrrev_i32_e32 v1, 31, v0
	v_lshl_add_u64 v[2:3], v[0:1], 4, s[92:93]
	s_mov_b64 s[4:5], 0x1f0000
	v_lshl_add_u64 v[2:3], v[2:3], 0, s[4:5]
	v_lshl_add_u32 v1, v0, 4, 0
	s_mov_b64 s[24:25], 0x2000
	global_load_dwordx4 v[100:103], v[2:3], off
	v_lshl_add_u64 v[2:3], v[2:3], 0, s[24:25]
	global_load_dwordx4 v[104:107], v[2:3], off
	v_lshl_add_u64 v[2:3], v[2:3], 0, s[24:25]
	global_load_dwordx4 v[108:111], v[2:3], off
	v_lshl_add_u64 v[2:3], v[2:3], 0, s[24:25]
	global_load_dwordx4 v[112:115], v[2:3], off
	v_lshl_add_u64 v[2:3], v[2:3], 0, s[24:25]
	global_load_dwordx4 v[116:119], v[2:3], off
	v_lshl_add_u64 v[2:3], v[2:3], 0, s[24:25]
	global_load_dwordx4 v[120:123], v[2:3], off
	v_lshl_add_u64 v[2:3], v[2:3], 0, s[24:25]
	global_load_dwordx4 v[124:127], v[2:3], off
	v_lshl_add_u64 v[2:3], v[2:3], 0, s[24:25]
	global_load_dwordx4 v[128:131], v[2:3], off
	v_lshl_add_u64 v[2:3], v[2:3], 0, s[24:25]
	global_load_dwordx4 v[132:135], v[2:3], off
	v_lshl_add_u64 v[2:3], v[2:3], 0, s[24:25]
	global_load_dwordx4 v[136:139], v[2:3], off
	v_lshl_add_u64 v[2:3], v[2:3], 0, s[24:25]
	global_load_dwordx4 v[140:143], v[2:3], off
	v_lshl_add_u64 v[2:3], v[2:3], 0, s[24:25]
	global_load_dwordx4 v[144:147], v[2:3], off
	s_waitcnt vmcnt(0)
	ds_write_b128 v1, v[100:103]
	ds_write_b128 v1, v[104:107] offset:8192
	ds_write_b128 v1, v[108:111] offset:16384
	ds_write_b128 v1, v[112:115] offset:24576
	ds_write_b128 v1, v[116:119] offset:32768
	ds_write_b128 v1, v[120:123] offset:40960
	ds_write_b128 v1, v[124:127] offset:49152
	ds_write_b128 v1, v[128:131] offset:57344
	v_add_u32_e32 v4, 0x10000, v1
	ds_write_b128 v4, v[132:135]
	ds_write_b128 v4, v[136:139] offset:8192
	ds_write_b128 v4, v[140:143] offset:16384
	ds_write_b128 v4, v[144:147] offset:24576

.Lgprio_skip3:
	s_bitcmp1_b32 s2, 0
	s_cbranch_scc0 .Ldf_skip_p6
	v_writelane_b32 v234, s0, 0
	v_writelane_b32 v234, s1, 1
	v_writelane_b32 v234, s2, 2
	v_writelane_b32 v234, s3, 3
	v_writelane_b32 v234, s4, 4
	v_writelane_b32 v234, s5, 5
	v_writelane_b32 v234, s6, 6
	v_writelane_b32 v234, s7, 7
	v_writelane_b32 v234, s8, 8
	v_writelane_b32 v234, s9, 9
	v_writelane_b32 v234, s10, 10
	v_writelane_b32 v234, s11, 11
	v_writelane_b32 v234, s12, 12
	v_writelane_b32 v234, s13, 13
	v_writelane_b32 v234, s14, 14
	v_writelane_b32 v234, s15, 15
	v_writelane_b32 v234, s16, 16
	v_writelane_b32 v234, s17, 17
	v_writelane_b32 v234, s18, 18
	v_writelane_b32 v234, s19, 19
	v_writelane_b32 v234, s20, 20
	v_writelane_b32 v234, s21, 21
	v_writelane_b32 v234, s22, 22
	v_writelane_b32 v234, s23, 23
	v_writelane_b32 v234, s24, 24
	v_writelane_b32 v234, s25, 25
	v_writelane_b32 v234, s26, 26
	v_writelane_b32 v234, s27, 27
	v_writelane_b32 v234, s28, 28
	v_writelane_b32 v234, s29, 29
	v_writelane_b32 v234, s30, 30
	v_writelane_b32 v234, s31, 31
	v_writelane_b32 v234, s32, 32
	v_writelane_b32 v234, s33, 33
	v_writelane_b32 v234, s34, 34
	v_writelane_b32 v234, s35, 35
	v_writelane_b32 v234, s36, 36
	v_writelane_b32 v234, s37, 37
	v_writelane_b32 v234, s38, 38
	v_writelane_b32 v234, s39, 39
	v_writelane_b32 v234, s40, 40
	v_writelane_b32 v234, s41, 41
	v_writelane_b32 v234, s42, 42
	v_writelane_b32 v234, s43, 43
	v_writelane_b32 v234, s44, 44
	v_writelane_b32 v234, s45, 45
	v_writelane_b32 v234, s46, 46
	v_writelane_b32 v234, s47, 47
	v_writelane_b32 v234, s48, 48
	v_writelane_b32 v234, s49, 49
	v_writelane_b32 v234, s50, 50
	v_writelane_b32 v234, s51, 51
	v_writelane_b32 v234, s52, 52
	v_writelane_b32 v234, s53, 53
	v_writelane_b32 v234, s54, 54
	v_writelane_b32 v234, s55, 55
	v_writelane_b32 v234, s56, 56
	v_writelane_b32 v234, s57, 57
	v_writelane_b32 v234, s58, 58
	v_writelane_b32 v234, s59, 59
	v_writelane_b32 v234, s60, 60
	v_writelane_b32 v234, s61, 61
	v_writelane_b32 v234, s62, 62
	v_writelane_b32 v234, s63, 63
	v_writelane_b32 v235, s64, 0
	v_writelane_b32 v235, s65, 1
	v_writelane_b32 v235, s66, 2
	v_writelane_b32 v235, s67, 3
	v_writelane_b32 v235, s68, 4
	v_writelane_b32 v235, s69, 5
	v_writelane_b32 v235, s70, 6
	v_writelane_b32 v235, s71, 7
	v_writelane_b32 v235, s72, 8
	v_writelane_b32 v235, s73, 9
	v_writelane_b32 v235, s74, 10
	v_writelane_b32 v235, s75, 11
	v_writelane_b32 v235, s76, 12
	v_writelane_b32 v235, s77, 13
	v_writelane_b32 v235, s78, 14
	v_writelane_b32 v235, s79, 15
	v_writelane_b32 v235, s80, 16
	v_writelane_b32 v235, s81, 17
	v_writelane_b32 v235, s82, 18
	v_writelane_b32 v235, s83, 19
	v_writelane_b32 v235, s84, 20
	v_writelane_b32 v235, s85, 21
	v_writelane_b32 v235, s86, 22
	v_writelane_b32 v235, s87, 23
	v_writelane_b32 v235, s88, 24
	v_writelane_b32 v235, s89, 25
	v_writelane_b32 v235, s90, 26
	v_writelane_b32 v235, s91, 27
	v_writelane_b32 v235, s92, 28
	v_writelane_b32 v235, s93, 29
	v_writelane_b32 v235, s94, 30
	v_writelane_b32 v235, s95, 31
	v_writelane_b32 v235, s96, 32
	v_writelane_b32 v235, s97, 33
	v_writelane_b32 v235, vcc_lo, 34
	v_writelane_b32 v235, vcc_hi, 35
	v_readlane_b32 s70, v233, 45
	v_readlane_b32 s71, v233, 46
	s_add_u32 s22, s92, 0x4500000
	s_addc_u32 s23, s93, 0
	s_add_u32 s40, s92, 0x1400000
	s_addc_u32 s41, s93, 0
	v_mov_b32_e32 v0, v210
	s_nop 0
	v_readfirstlane_b32 s1, v0
	s_nop 3
	s_ashr_i32 s13, s1, 6
	s_lshr_b32 s0, s2, 1
	s_lshl_b32 s0, s0, 3
	s_add_i32 s33, s13, s0
	s_addk_i32 s33, 0x1c00
	s_movk_i32 s12, 0x80
	s_movk_i32 s101, 0x2400
	s_mov_b32 s100, 5
	s_branch .Lp3t_setup

.LBB0_797:
	ds_read_b128 v[148:151], v179
	ds_read_b128 v[152:155], v179 offset:1024
	ds_read_b128 v[156:159], v179 offset:2048
	ds_read_b128 v[160:163], v179 offset:3072
	ds_read_b128 v[164:167], v180
	ds_read_b128 v[168:171], v180 offset:1024
	ds_read_b128 v[172:175], v180 offset:2048
	ds_read_b128 v[182:185], v180 offset:3072
	s_add_u32 s24, s38, 0xfff80080
	s_addc_u32 s25, s39, -1
	s_cmp_eq_u32 s76, 28
	s_cselect_b32 s49, s5, s25
	s_cselect_b32 s48, s15, s24
	s_cselect_b32 s47, s50, s67
	s_cselect_b32 s46, s51, s65
	v_lshl_add_u64 v[176:177], s[38:39], 0, v[140:141]
	s_add_i32 m0, s80, 0xc000
	ds_read_b128 v[186:189], v181
	ds_read_b128 v[190:193], v181 offset:1024
	ds_read_b128 v[194:197], v181 offset:2048
	ds_read_b128 v[198:201], v181 offset:3072
	ds_read_b128 v[202:205], v181 offset:4096
	ds_read_b128 v[206:209], v181 offset:5120
	ds_read_b128 v[212:215], v181 offset:6144
	ds_read_b128 v[216:219], v181 offset:7168
	global_load_lds_dwordx4 v[176:177], off
	v_lshl_add_u64 v[176:177], s[38:39], 0, v[142:143]
	s_add_i32 m0, s80, 0xe000
	s_nop 0
	global_load_lds_dwordx4 v[176:177], off
	s_waitcnt vmcnt(8)
	s_waitcnt lgkmcnt(0)
	s_barrier
	s_waitcnt lgkmcnt(0)
	v_mfma_f32_16x16x32_bf16 v[124:127], v[148:151], v[186:189], v[124:127]
	v_mfma_f32_16x16x32_bf16 v[120:123], v[156:159], v[186:189], v[120:123]
	v_mfma_f32_16x16x32_bf16 v[116:119], v[148:151], v[194:197], v[116:119]
	v_mfma_f32_16x16x32_bf16 v[112:115], v[156:159], v[194:197], v[112:115]
	v_mfma_f32_16x16x32_bf16 v[108:111], v[148:151], v[202:205], v[108:111]
	v_mfma_f32_16x16x32_bf16 v[104:107], v[156:159], v[202:205], v[104:107]
	v_mfma_f32_16x16x32_bf16 v[100:103], v[148:151], v[212:215], v[100:103]
	v_mfma_f32_16x16x32_bf16 v[96:99], v[156:159], v[212:215], v[96:99]
	v_mfma_f32_16x16x32_bf16 v[124:127], v[152:155], v[190:193], v[124:127]
	v_mfma_f32_16x16x32_bf16 v[120:123], v[160:163], v[190:193], v[120:123]
	v_mfma_f32_16x16x32_bf16 v[116:119], v[152:155], v[198:201], v[116:119]
	v_mfma_f32_16x16x32_bf16 v[112:115], v[160:163], v[198:201], v[112:115]
	v_mfma_f32_16x16x32_bf16 v[108:111], v[152:155], v[206:209], v[108:111]
	v_mfma_f32_16x16x32_bf16 v[104:107], v[160:163], v[206:209], v[104:107]
	v_mfma_f32_16x16x32_bf16 v[100:103], v[152:155], v[216:219], v[100:103]
	v_mfma_f32_16x16x32_bf16 v[96:99], v[160:163], v[216:219], v[96:99]
	v_mfma_f32_16x16x32_bf16 v[60:63], v[164:167], v[186:189], v[60:63]
	v_mfma_f32_16x16x32_bf16 v[56:59], v[172:175], v[186:189], v[56:59]
	v_mfma_f32_16x16x32_bf16 v[52:55], v[164:167], v[194:197], v[52:55]
	v_mfma_f32_16x16x32_bf16 v[48:51], v[172:175], v[194:197], v[48:51]
	v_mfma_f32_16x16x32_bf16 v[44:47], v[164:167], v[202:205], v[44:47]
	v_mfma_f32_16x16x32_bf16 v[40:43], v[172:175], v[202:205], v[40:43]
	v_mfma_f32_16x16x32_bf16 v[36:39], v[164:167], v[212:215], v[36:39]
	v_mfma_f32_16x16x32_bf16 v[32:35], v[172:175], v[212:215], v[32:35]
	v_mfma_f32_16x16x32_bf16 v[60:63], v[168:171], v[190:193], v[60:63]
	v_mfma_f32_16x16x32_bf16 v[56:59], v[182:185], v[190:193], v[56:59]
	v_mfma_f32_16x16x32_bf16 v[52:55], v[168:171], v[198:201], v[52:55]
	v_mfma_f32_16x16x32_bf16 v[48:51], v[182:185], v[198:201], v[48:51]
	v_mfma_f32_16x16x32_bf16 v[44:47], v[168:171], v[206:209], v[44:47]
	v_mfma_f32_16x16x32_bf16 v[40:43], v[182:185], v[206:209], v[40:43]
	v_mfma_f32_16x16x32_bf16 v[36:39], v[168:171], v[216:219], v[36:39]
	v_mfma_f32_16x16x32_bf16 v[32:35], v[182:185], v[216:219], v[32:35]
	s_barrier
	s_add_i32 s24, s87, s33
	v_lshl_add_u64 v[176:177], s[46:47], 0, v[130:131]
	s_mov_b32 m0, s24
	ds_read_b128 v[186:189], v181 offset:16384
	ds_read_b128 v[190:193], v181 offset:17408
	ds_read_b128 v[194:197], v181 offset:18432
	ds_read_b128 v[198:201], v181 offset:19456
	ds_read_b128 v[202:205], v181 offset:20480
	ds_read_b128 v[206:209], v181 offset:21504
	ds_read_b128 v[212:215], v181 offset:22528
	ds_read_b128 v[216:219], v181 offset:23552
	global_load_lds_dwordx4 v[176:177], off
	s_add_i32 m0, s24, 0x2000
	s_add_u32 s24, s46, 0x80000
	v_lshl_add_u64 v[220:221], s[46:47], 0, v[134:135]
	s_addc_u32 s25, s47, 0
	s_add_i32 s26, s88, s33
	global_load_lds_dwordx4 v[220:221], off
	v_lshl_add_u64 v[222:223], s[24:25], 0, v[130:131]
	s_mov_b32 m0, s26
	v_lshl_add_u64 v[224:225], s[48:49], 0, v[132:133]
	global_load_lds_dwordx4 v[222:223], off
	v_lshl_add_u64 v[222:223], s[24:25], 0, v[134:135]
	s_add_i32 m0, s26, 0x2000
	s_nop 0
	global_load_lds_dwordx4 v[222:223], off
	v_lshl_add_u64 v[222:223], s[48:49], 0, v[128:129]
	s_mov_b32 m0, s80
	s_nop 0
	global_load_lds_dwordx4 v[222:223], off
	s_mov_b32 m0, s81
	s_nop 0
	global_load_lds_dwordx4 v[224:225], off
	s_waitcnt vmcnt(8)
	s_waitcnt lgkmcnt(0)
	s_barrier
	s_waitcnt lgkmcnt(0)
	v_mfma_f32_16x16x32_bf16 v[92:95], v[148:151], v[186:189], v[92:95]
	v_mfma_f32_16x16x32_bf16 v[88:91], v[156:159], v[186:189], v[88:91]
	v_mfma_f32_16x16x32_bf16 v[84:87], v[148:151], v[194:197], v[84:87]
	v_mfma_f32_16x16x32_bf16 v[80:83], v[156:159], v[194:197], v[80:83]
	v_mfma_f32_16x16x32_bf16 v[76:79], v[148:151], v[202:205], v[76:79]
	v_mfma_f32_16x16x32_bf16 v[72:75], v[156:159], v[202:205], v[72:75]
	v_mfma_f32_16x16x32_bf16 v[68:71], v[148:151], v[212:215], v[68:71]
	v_mfma_f32_16x16x32_bf16 v[64:67], v[156:159], v[212:215], v[64:67]
	v_mfma_f32_16x16x32_bf16 v[92:95], v[152:155], v[190:193], v[92:95]
	v_mfma_f32_16x16x32_bf16 v[88:91], v[160:163], v[190:193], v[88:91]
	v_mfma_f32_16x16x32_bf16 v[84:87], v[152:155], v[198:201], v[84:87]
	v_mfma_f32_16x16x32_bf16 v[80:83], v[160:163], v[198:201], v[80:83]
	v_mfma_f32_16x16x32_bf16 v[76:79], v[152:155], v[206:209], v[76:79]
	v_mfma_f32_16x16x32_bf16 v[72:75], v[160:163], v[206:209], v[72:75]
	v_mfma_f32_16x16x32_bf16 v[68:71], v[152:155], v[216:219], v[68:71]
	v_mfma_f32_16x16x32_bf16 v[64:67], v[160:163], v[216:219], v[64:67]
	v_mfma_f32_16x16x32_bf16 v[28:31], v[164:167], v[186:189], v[28:31]
	v_mfma_f32_16x16x32_bf16 v[24:27], v[172:175], v[186:189], v[24:27]
	v_mfma_f32_16x16x32_bf16 v[20:23], v[164:167], v[194:197], v[20:23]
	v_mfma_f32_16x16x32_bf16 v[16:19], v[172:175], v[194:197], v[16:19]
	v_mfma_f32_16x16x32_bf16 v[12:15], v[164:167], v[202:205], v[12:15]
	v_mfma_f32_16x16x32_bf16 v[8:11], v[172:175], v[202:205], v[8:11]
	v_mfma_f32_16x16x32_bf16 v[4:7], v[164:167], v[212:215], v[4:7]
	v_mfma_f32_16x16x32_bf16 v[0:3], v[172:175], v[212:215], v[0:3]
	v_mfma_f32_16x16x32_bf16 v[28:31], v[168:171], v[190:193], v[28:31]
	v_mfma_f32_16x16x32_bf16 v[24:27], v[182:185], v[190:193], v[24:27]
	v_mfma_f32_16x16x32_bf16 v[20:23], v[168:171], v[198:201], v[20:23]
	v_mfma_f32_16x16x32_bf16 v[16:19], v[182:185], v[198:201], v[16:19]
	v_mfma_f32_16x16x32_bf16 v[12:15], v[168:171], v[206:209], v[12:15]
	v_mfma_f32_16x16x32_bf16 v[8:11], v[182:185], v[206:209], v[8:11]
	v_mfma_f32_16x16x32_bf16 v[4:7], v[168:171], v[216:219], v[4:7]
	v_mfma_f32_16x16x32_bf16 v[0:3], v[182:185], v[216:219], v[0:3]
	s_barrier
	s_add_i32 s26, 0, 0x18000
	v_add_u32_e32 v136, s26, v178
	s_add_i32 s27, 0, 0x1c000
	ds_read_b128 v[148:151], v136
	ds_read_b128 v[152:155], v136 offset:1024
	ds_read_b128 v[156:159], v136 offset:2048
	ds_read_b128 v[160:163], v136 offset:3072
	v_add_u32_e32 v136, s27, v178
	ds_read_b128 v[164:167], v136
	ds_read_b128 v[168:171], v136 offset:1024
	ds_read_b128 v[172:175], v136 offset:2048
	ds_read_b128 v[182:185], v136 offset:3072
	s_add_u32 s24, s48, 0x80000
	s_addc_u32 s25, s49, 0
	s_mov_b32 m0, s82
	v_lshl_add_u64 v[226:227], s[24:25], 0, v[128:129]
	ds_read_b128 v[186:189], v181 offset:32768
	ds_read_b128 v[190:193], v181 offset:33792
	ds_read_b128 v[194:197], v181 offset:34816
	ds_read_b128 v[198:201], v181 offset:35840
	ds_read_b128 v[202:205], v181 offset:36864
	ds_read_b128 v[206:209], v181 offset:37888
	ds_read_b128 v[212:215], v181 offset:38912
	ds_read_b128 v[216:219], v181 offset:39936
	global_load_lds_dwordx4 v[226:227], off
	v_lshl_add_u64 v[226:227], s[24:25], 0, v[132:133]
	s_mov_b32 m0, s83
	s_nop 0
	global_load_lds_dwordx4 v[226:227], off
	s_waitcnt vmcnt(8)
	s_waitcnt lgkmcnt(0)
	s_barrier
	s_waitcnt lgkmcnt(0)
	v_mfma_f32_16x16x32_bf16 v[124:127], v[148:151], v[186:189], v[124:127]
	v_mfma_f32_16x16x32_bf16 v[120:123], v[156:159], v[186:189], v[120:123]
	v_mfma_f32_16x16x32_bf16 v[116:119], v[148:151], v[194:197], v[116:119]
	v_mfma_f32_16x16x32_bf16 v[112:115], v[156:159], v[194:197], v[112:115]
	v_mfma_f32_16x16x32_bf16 v[108:111], v[148:151], v[202:205], v[108:111]
	v_mfma_f32_16x16x32_bf16 v[104:107], v[156:159], v[202:205], v[104:107]
	v_mfma_f32_16x16x32_bf16 v[100:103], v[148:151], v[212:215], v[100:103]
	v_mfma_f32_16x16x32_bf16 v[96:99], v[156:159], v[212:215], v[96:99]
	v_mfma_f32_16x16x32_bf16 v[124:127], v[152:155], v[190:193], v[124:127]
	v_mfma_f32_16x16x32_bf16 v[120:123], v[160:163], v[190:193], v[120:123]
	v_mfma_f32_16x16x32_bf16 v[116:119], v[152:155], v[198:201], v[116:119]
	v_mfma_f32_16x16x32_bf16 v[112:115], v[160:163], v[198:201], v[112:115]
	v_mfma_f32_16x16x32_bf16 v[108:111], v[152:155], v[206:209], v[108:111]
	v_mfma_f32_16x16x32_bf16 v[104:107], v[160:163], v[206:209], v[104:107]
	v_mfma_f32_16x16x32_bf16 v[100:103], v[152:155], v[216:219], v[100:103]
	v_mfma_f32_16x16x32_bf16 v[96:99], v[160:163], v[216:219], v[96:99]
	v_mfma_f32_16x16x32_bf16 v[60:63], v[164:167], v[186:189], v[60:63]
	v_mfma_f32_16x16x32_bf16 v[56:59], v[172:175], v[186:189], v[56:59]
	v_mfma_f32_16x16x32_bf16 v[52:55], v[164:167], v[194:197], v[52:55]
	v_mfma_f32_16x16x32_bf16 v[48:51], v[172:175], v[194:197], v[48:51]
	v_mfma_f32_16x16x32_bf16 v[44:47], v[164:167], v[202:205], v[44:47]
	v_mfma_f32_16x16x32_bf16 v[40:43], v[172:175], v[202:205], v[40:43]
	v_mfma_f32_16x16x32_bf16 v[36:39], v[164:167], v[212:215], v[36:39]
	v_mfma_f32_16x16x32_bf16 v[32:35], v[172:175], v[212:215], v[32:35]
	v_mfma_f32_16x16x32_bf16 v[60:63], v[168:171], v[190:193], v[60:63]
	v_mfma_f32_16x16x32_bf16 v[56:59], v[182:185], v[190:193], v[56:59]
	v_mfma_f32_16x16x32_bf16 v[52:55], v[168:171], v[198:201], v[52:55]
	v_mfma_f32_16x16x32_bf16 v[48:51], v[182:185], v[198:201], v[48:51]
	v_mfma_f32_16x16x32_bf16 v[44:47], v[168:171], v[206:209], v[44:47]
	v_mfma_f32_16x16x32_bf16 v[40:43], v[182:185], v[206:209], v[40:43]
	v_mfma_f32_16x16x32_bf16 v[36:39], v[168:171], v[216:219], v[36:39]
	v_mfma_f32_16x16x32_bf16 v[32:35], v[182:185], v[216:219], v[32:35]
	s_barrier
	s_add_i32 s24, s26, s33
	v_lshl_add_u64 v[176:177], v[176:177], 0, s[60:61]
	s_mov_b32 m0, s24
	ds_read_b128 v[186:189], v181 offset:49152
	ds_read_b128 v[190:193], v181 offset:50176
	ds_read_b128 v[194:197], v181 offset:51200
	ds_read_b128 v[198:201], v181 offset:52224
	ds_read_b128 v[202:205], v181 offset:53248
	ds_read_b128 v[206:209], v181 offset:54272
	ds_read_b128 v[212:215], v181 offset:55296
	ds_read_b128 v[216:219], v181 offset:56320
	global_load_lds_dwordx4 v[176:177], off
	s_add_i32 m0, s24, 0x2000
	s_add_u32 s24, s46, 0x80080
	v_lshl_add_u64 v[176:177], v[220:221], 0, s[60:61]
	s_addc_u32 s25, s47, 0
	s_add_i32 s26, s27, s33
	global_load_lds_dwordx4 v[176:177], off
	v_lshl_add_u64 v[176:177], s[24:25], 0, v[130:131]
	s_mov_b32 m0, s26
	s_nop 0
	global_load_lds_dwordx4 v[176:177], off
	v_lshl_add_u64 v[176:177], s[24:25], 0, v[134:135]
	s_add_i32 m0, s26, 0x2000
	s_nop 0
	global_load_lds_dwordx4 v[176:177], off
	v_lshl_add_u64 v[176:177], v[222:223], 0, s[60:61]
	s_mov_b32 m0, s85
	s_nop 0
	global_load_lds_dwordx4 v[176:177], off
	v_lshl_add_u64 v[176:177], v[224:225], 0, s[60:61]
	s_mov_b32 m0, s86
	s_nop 0
	global_load_lds_dwordx4 v[176:177], off
	s_waitcnt vmcnt(8)
	s_waitcnt lgkmcnt(0)
	s_barrier
	s_waitcnt lgkmcnt(0)
	v_mfma_f32_16x16x32_bf16 v[92:95], v[148:151], v[186:189], v[92:95]
	v_mfma_f32_16x16x32_bf16 v[88:91], v[156:159], v[186:189], v[88:91]
	v_mfma_f32_16x16x32_bf16 v[84:87], v[148:151], v[194:197], v[84:87]
	v_mfma_f32_16x16x32_bf16 v[80:83], v[156:159], v[194:197], v[80:83]
	v_mfma_f32_16x16x32_bf16 v[76:79], v[148:151], v[202:205], v[76:79]
	v_mfma_f32_16x16x32_bf16 v[72:75], v[156:159], v[202:205], v[72:75]
	v_mfma_f32_16x16x32_bf16 v[68:71], v[148:151], v[212:215], v[68:71]
	v_mfma_f32_16x16x32_bf16 v[64:67], v[156:159], v[212:215], v[64:67]
	v_mfma_f32_16x16x32_bf16 v[92:95], v[152:155], v[190:193], v[92:95]
	v_mfma_f32_16x16x32_bf16 v[88:91], v[160:163], v[190:193], v[88:91]
	v_mfma_f32_16x16x32_bf16 v[84:87], v[152:155], v[198:201], v[84:87]
	v_mfma_f32_16x16x32_bf16 v[80:83], v[160:163], v[198:201], v[80:83]
	v_mfma_f32_16x16x32_bf16 v[76:79], v[152:155], v[206:209], v[76:79]
	v_mfma_f32_16x16x32_bf16 v[72:75], v[160:163], v[206:209], v[72:75]
	v_mfma_f32_16x16x32_bf16 v[68:71], v[152:155], v[216:219], v[68:71]
	v_mfma_f32_16x16x32_bf16 v[64:67], v[160:163], v[216:219], v[64:67]
	v_mfma_f32_16x16x32_bf16 v[28:31], v[164:167], v[186:189], v[28:31]
	v_mfma_f32_16x16x32_bf16 v[24:27], v[172:175], v[186:189], v[24:27]
	v_mfma_f32_16x16x32_bf16 v[20:23], v[164:167], v[194:197], v[20:23]
	v_mfma_f32_16x16x32_bf16 v[16:19], v[172:175], v[194:197], v[16:19]
	v_mfma_f32_16x16x32_bf16 v[12:15], v[164:167], v[202:205], v[12:15]
	v_mfma_f32_16x16x32_bf16 v[8:11], v[172:175], v[202:205], v[8:11]
	v_mfma_f32_16x16x32_bf16 v[4:7], v[164:167], v[212:215], v[4:7]
	v_mfma_f32_16x16x32_bf16 v[0:3], v[172:175], v[212:215], v[0:3]
	v_mfma_f32_16x16x32_bf16 v[28:31], v[168:171], v[190:193], v[28:31]
	v_mfma_f32_16x16x32_bf16 v[24:27], v[182:185], v[190:193], v[24:27]
	v_mfma_f32_16x16x32_bf16 v[20:23], v[168:171], v[198:201], v[20:23]
	v_mfma_f32_16x16x32_bf16 v[16:19], v[182:185], v[198:201], v[16:19]
	v_mfma_f32_16x16x32_bf16 v[12:15], v[168:171], v[206:209], v[12:15]
	v_mfma_f32_16x16x32_bf16 v[8:11], v[182:185], v[206:209], v[8:11]
	v_mfma_f32_16x16x32_bf16 v[4:7], v[168:171], v[216:219], v[4:7]
	v_mfma_f32_16x16x32_bf16 v[0:3], v[182:185], v[216:219], v[0:3]
	s_barrier
	s_add_i32 s76, s76, 2
	s_add_u32 s38, s38, 0x100
	s_addc_u32 s39, s39, 0
	s_add_u32 s65, s65, 0x100
	s_addc_u32 s67, s67, 0
	s_cmp_gt_u32 s76, 29
	s_cbranch_scc0 .LBB0_797
	s_and_b64 vcc, exec, s[62:63]
	s_cbranch_vccz .LBB0_800
	s_barrier

.LBB0_1034:
	s_or_b64 exec, exec, s[0:1]
	s_setprio 0
	v_readlane_b32 s52, v232, 54
	s_add_u32 s78, s92, 0x120000
	v_readlane_b32 s53, v232, 55
	s_addc_u32 s79, s93, 0
	s_and_b64 vcc, exec, s[52:53]
	s_waitcnt lgkmcnt(0)
	s_barrier
	s_cbranch_vccnz .LBB0_1074
	s_lshl_b32 s0, s2, 5
	s_and_b32 s0, s0, 0xe0
	s_ashr_i32 s1, s2, 3
	s_add_i32 s0, s0, s1
	s_and_b32 s25, s1, 7
	s_ashr_i32 s24, s0, 3
	s_cmp_lt_u32 s25, 4
	s_mul_i32 s25, s25, 15
	s_cselect_b64 s[38:39], -1, 0
	s_sub_i32 s4, s25, 60
	s_and_b64 s[0:1], s[38:39], exec
	s_mov_b32 s1, 0x814c115
	s_cselect_b32 s43, s1, 0x94eaaa3
	s_mov_b32 s1, 0xd0478067
	s_cselect_b32 s0, s25, s4
	s_cselect_b32 s42, s1, 0x62bb258e
	s_lshr_b64 s[4:5], s[42:43], s0
	s_mul_i32 s24, s24, 3
	s_bfe_u32 s0, s4, 0x20003
	s_add_i32 s14, s0, s24
	s_and_b32 s51, s4, 7
	s_ashr_i32 s15, s14, 31
	v_mov_b32_e32 v4, v210
	s_movk_i32 s5, 0x100
	s_lshl_b64 s[0:1], s[14:15], 11
	s_lshl_b32 s33, s51, 8
	v_mov_b32_e32 v0, 0
	v_cmp_gt_i32_e32 vcc, s5, v4
	v_ashrrev_i32_e32 v5, 31, v4
	v_mov_b32_e32 v12, 0
	v_mov_b32_e32 v16, 0
	v_mov_b32_e32 v17, 0
	v_mov_b32_e32 v18, 0
	v_mov_b32_e32 v19, 0
	v_mov_b32_e32 v20, 0
	v_mov_b32_e32 v21, 0
	v_mov_b32_e32 v22, 0
	v_mov_b32_e32 v23, 0
	v_mov_b32_e32 v24, 0
	v_mov_b32_e32 v25, 0
	v_mov_b32_e32 v26, 0
	v_mov_b32_e32 v27, 0
	s_and_saveexec_b64 s[40:41], vcc
	s_cbranch_execz .LBB0_1037
	s_lshl_b64 s[26:27], s[0:1], 2
	v_readlane_b32 s28, v233, 37
	v_readlane_b32 s29, v233, 38
	s_add_u32 s5, s28, s26
	s_addc_u32 s27, s29, s27
	s_lshl_b32 s26, s33, 2
	s_add_u32 s26, s5, s26
	s_addc_u32 s27, s27, 0
	v_lshl_add_u64 v[2:3], v[4:5], 2, s[26:27]
	global_load_dword v12, v[2:3], off

.Lgprio_skip4:
	v_mov_b32_e32 v12, v210
	s_waitcnt lgkmcnt(0)
	s_barrier
	s_and_b64 vcc, exec, s[34:35]
	v_readfirstlane_b32 s24, v12
	s_cbranch_vccnz .LBB0_1226
	v_readlane_b32 s0, v232, 58
	s_mul_i32 s4, s0, 0x41
	s_lshl_b32 s5, s0, 6
	v_readlane_b32 s0, v232, 59
	v_readlane_b32 s1, v232, 60
	s_and_b64 s[0:1], s[0:1], exec
	s_cselect_b32 s0, s4, s5
	v_readlane_b32 s1, v232, 61
	s_add_i32 s0, s0, s1
	s_ashr_i32 s1, s0, 31
	s_lshr_b32 s1, s1, 27
	s_add_i32 s1, s0, s1
	s_ashr_i32 s4, s1, 5
	s_and_b32 s1, s1, 0xffe0
	s_sub_i32 s0, s0, s1
	s_bfe_i32 s1, s0, 0x80000
	s_bfe_u32 s1, s1, 0x2000d
	s_add_i32 s1, s0, s1
	s_bfe_i32 s5, s1, 0x80000
	s_and_b32 s1, s1, 0xfc
	s_sub_i32 s0, s0, s1
	s_lshl_b32 s4, s4, 2
	s_sext_i32_i16 s5, s5
	s_sext_i32_i8 s0, s0
	s_add_i32 s52, s4, s0
	s_ashr_i32 s14, s5, 2

.LBB0_1239:
	ds_read_b128 v[144:147], v151
	ds_read_b128 v[154:157], v151 offset:1024
	ds_read_b128 v[158:161], v151 offset:2048
	ds_read_b128 v[162:165], v151 offset:3072
	ds_read_b128 v[166:169], v152
	ds_read_b128 v[170:173], v152 offset:1024
	ds_read_b128 v[174:177], v152 offset:2048
	ds_read_b128 v[178:181], v152 offset:3072
	s_add_u32 s24, s54, 0xfff80080
	s_addc_u32 s25, s55, -1
	s_cmp_eq_u32 s77, 28
	s_cselect_b32 s59, s15, s25
	s_cselect_b32 s58, s47, s24
	s_cselect_b32 s57, s45, s76
	s_cselect_b32 s56, s68, s69
	v_lshl_add_u64 v[216:217], s[54:55], 0, v[136:137]
	s_add_i32 m0, s53, 0xc000
	ds_read_b128 v[182:185], v153
	ds_read_b128 v[186:189], v153 offset:1024
	ds_read_b128 v[190:193], v153 offset:2048
	ds_read_b128 v[194:197], v153 offset:3072
	ds_read_b128 v[198:201], v153 offset:4096
	ds_read_b128 v[202:205], v153 offset:5120
	ds_read_b128 v[206:209], v153 offset:6144
	ds_read_b128 v[212:215], v153 offset:7168
	global_load_lds_dwordx4 v[216:217], off
	v_lshl_add_u64 v[216:217], s[54:55], 0, v[138:139]
	s_add_i32 m0, s53, 0xe000
	s_nop 0
	global_load_lds_dwordx4 v[216:217], off
	s_waitcnt vmcnt(8)
	s_waitcnt lgkmcnt(0)
	s_barrier
	s_waitcnt lgkmcnt(0)
	v_mfma_f32_16x16x32_bf16 v[124:127], v[144:147], v[182:185], v[124:127]
	v_mfma_f32_16x16x32_bf16 v[120:123], v[158:161], v[182:185], v[120:123]
	v_mfma_f32_16x16x32_bf16 v[108:111], v[144:147], v[190:193], v[108:111]
	v_mfma_f32_16x16x32_bf16 v[104:107], v[158:161], v[190:193], v[104:107]
	v_mfma_f32_16x16x32_bf16 v[92:95], v[144:147], v[198:201], v[92:95]
	v_mfma_f32_16x16x32_bf16 v[88:91], v[158:161], v[198:201], v[88:91]
	v_mfma_f32_16x16x32_bf16 v[76:79], v[144:147], v[206:209], v[76:79]
	v_mfma_f32_16x16x32_bf16 v[72:75], v[158:161], v[206:209], v[72:75]
	v_mfma_f32_16x16x32_bf16 v[124:127], v[154:157], v[186:189], v[124:127]
	v_mfma_f32_16x16x32_bf16 v[120:123], v[162:165], v[186:189], v[120:123]
	v_mfma_f32_16x16x32_bf16 v[108:111], v[154:157], v[194:197], v[108:111]
	v_mfma_f32_16x16x32_bf16 v[104:107], v[162:165], v[194:197], v[104:107]
	v_mfma_f32_16x16x32_bf16 v[92:95], v[154:157], v[202:205], v[92:95]
	v_mfma_f32_16x16x32_bf16 v[88:91], v[162:165], v[202:205], v[88:91]
	v_mfma_f32_16x16x32_bf16 v[76:79], v[154:157], v[212:215], v[76:79]
	v_mfma_f32_16x16x32_bf16 v[72:75], v[162:165], v[212:215], v[72:75]
	v_mfma_f32_16x16x32_bf16 v[116:119], v[166:169], v[182:185], v[116:119]
	v_mfma_f32_16x16x32_bf16 v[112:115], v[174:177], v[182:185], v[112:115]
	v_mfma_f32_16x16x32_bf16 v[100:103], v[166:169], v[190:193], v[100:103]
	v_mfma_f32_16x16x32_bf16 v[96:99], v[174:177], v[190:193], v[96:99]
	v_mfma_f32_16x16x32_bf16 v[84:87], v[166:169], v[198:201], v[84:87]
	v_mfma_f32_16x16x32_bf16 v[80:83], v[174:177], v[198:201], v[80:83]
	v_mfma_f32_16x16x32_bf16 v[68:71], v[166:169], v[206:209], v[68:71]
	v_mfma_f32_16x16x32_bf16 v[64:67], v[174:177], v[206:209], v[64:67]
	v_mfma_f32_16x16x32_bf16 v[116:119], v[170:173], v[186:189], v[116:119]
	v_mfma_f32_16x16x32_bf16 v[112:115], v[178:181], v[186:189], v[112:115]
	v_mfma_f32_16x16x32_bf16 v[100:103], v[170:173], v[194:197], v[100:103]
	v_mfma_f32_16x16x32_bf16 v[96:99], v[178:181], v[194:197], v[96:99]
	v_mfma_f32_16x16x32_bf16 v[84:87], v[170:173], v[202:205], v[84:87]
	v_mfma_f32_16x16x32_bf16 v[80:83], v[178:181], v[202:205], v[80:83]
	v_mfma_f32_16x16x32_bf16 v[68:71], v[170:173], v[212:215], v[68:71]
	v_mfma_f32_16x16x32_bf16 v[64:67], v[178:181], v[212:215], v[64:67]
	s_barrier
	s_add_i32 s24, s66, s33
	v_lshl_add_u64 v[216:217], s[56:57], 0, v[130:131]
	s_mov_b32 m0, s24
	ds_read_b128 v[182:185], v153 offset:16384
	ds_read_b128 v[186:189], v153 offset:17408
	ds_read_b128 v[190:193], v153 offset:18432
	ds_read_b128 v[194:197], v153 offset:19456
	ds_read_b128 v[198:201], v153 offset:20480
	ds_read_b128 v[202:205], v153 offset:21504
	ds_read_b128 v[206:209], v153 offset:22528
	ds_read_b128 v[212:215], v153 offset:23552
	global_load_lds_dwordx4 v[216:217], off
	s_add_i32 m0, s24, 0x2000
	s_add_u32 s24, s56, 0x80000
	v_lshl_add_u64 v[218:219], s[56:57], 0, v[134:135]
	s_addc_u32 s25, s57, 0
	s_add_i32 s26, s67, s33
	global_load_lds_dwordx4 v[218:219], off
	v_lshl_add_u64 v[220:221], s[24:25], 0, v[130:131]
	s_mov_b32 m0, s26
	v_lshl_add_u64 v[222:223], s[58:59], 0, v[132:133]
	global_load_lds_dwordx4 v[220:221], off
	v_lshl_add_u64 v[220:221], s[24:25], 0, v[134:135]
	s_add_i32 m0, s26, 0x2000
	s_nop 0
	global_load_lds_dwordx4 v[220:221], off
	v_lshl_add_u64 v[220:221], s[58:59], 0, v[128:129]
	s_mov_b32 m0, s53
	s_nop 0
	global_load_lds_dwordx4 v[220:221], off
	s_mov_b32 m0, s60
	s_nop 0
	global_load_lds_dwordx4 v[222:223], off
	s_waitcnt vmcnt(8)
	s_waitcnt lgkmcnt(0)
	s_barrier
	s_waitcnt lgkmcnt(0)
	v_mfma_f32_16x16x32_bf16 v[60:63], v[144:147], v[182:185], v[60:63]
	v_mfma_f32_16x16x32_bf16 v[56:59], v[158:161], v[182:185], v[56:59]
	v_mfma_f32_16x16x32_bf16 v[44:47], v[144:147], v[190:193], v[44:47]
	v_mfma_f32_16x16x32_bf16 v[40:43], v[158:161], v[190:193], v[40:43]
	v_mfma_f32_16x16x32_bf16 v[28:31], v[144:147], v[198:201], v[28:31]
	v_mfma_f32_16x16x32_bf16 v[24:27], v[158:161], v[198:201], v[24:27]
	v_mfma_f32_16x16x32_bf16 v[12:15], v[144:147], v[206:209], v[12:15]
	v_mfma_f32_16x16x32_bf16 v[8:11], v[158:161], v[206:209], v[8:11]
	v_mfma_f32_16x16x32_bf16 v[60:63], v[154:157], v[186:189], v[60:63]
	v_mfma_f32_16x16x32_bf16 v[56:59], v[162:165], v[186:189], v[56:59]
	v_mfma_f32_16x16x32_bf16 v[44:47], v[154:157], v[194:197], v[44:47]
	v_mfma_f32_16x16x32_bf16 v[40:43], v[162:165], v[194:197], v[40:43]
	v_mfma_f32_16x16x32_bf16 v[28:31], v[154:157], v[202:205], v[28:31]
	v_mfma_f32_16x16x32_bf16 v[24:27], v[162:165], v[202:205], v[24:27]
	v_mfma_f32_16x16x32_bf16 v[12:15], v[154:157], v[212:215], v[12:15]
	v_mfma_f32_16x16x32_bf16 v[8:11], v[162:165], v[212:215], v[8:11]
	v_mfma_f32_16x16x32_bf16 v[52:55], v[166:169], v[182:185], v[52:55]
	v_mfma_f32_16x16x32_bf16 v[48:51], v[174:177], v[182:185], v[48:51]
	v_mfma_f32_16x16x32_bf16 v[36:39], v[166:169], v[190:193], v[36:39]
	v_mfma_f32_16x16x32_bf16 v[32:35], v[174:177], v[190:193], v[32:35]
	v_mfma_f32_16x16x32_bf16 v[20:23], v[166:169], v[198:201], v[20:23]
	v_mfma_f32_16x16x32_bf16 v[16:19], v[174:177], v[198:201], v[16:19]
	v_mfma_f32_16x16x32_bf16 v[4:7], v[166:169], v[206:209], v[4:7]
	v_mfma_f32_16x16x32_bf16 v[0:3], v[174:177], v[206:209], v[0:3]
	v_mfma_f32_16x16x32_bf16 v[52:55], v[170:173], v[186:189], v[52:55]
	v_mfma_f32_16x16x32_bf16 v[48:51], v[178:181], v[186:189], v[48:51]
	v_mfma_f32_16x16x32_bf16 v[36:39], v[170:173], v[194:197], v[36:39]
	v_mfma_f32_16x16x32_bf16 v[32:35], v[178:181], v[194:197], v[32:35]
	v_mfma_f32_16x16x32_bf16 v[20:23], v[170:173], v[202:205], v[20:23]
	v_mfma_f32_16x16x32_bf16 v[16:19], v[178:181], v[202:205], v[16:19]
	v_mfma_f32_16x16x32_bf16 v[4:7], v[170:173], v[212:215], v[4:7]
	v_mfma_f32_16x16x32_bf16 v[0:3], v[178:181], v[212:215], v[0:3]
	s_barrier
	s_add_i32 s26, 0, 0x18000
	s_add_i32 s27, 0, 0x1c000
	v_add_u32_e32 v162, s26, v149
	v_add_u32_e32 v178, s27, v149
	ds_read_b128 v[144:147], v162
	ds_read_b128 v[154:157], v162 offset:1024
	ds_read_b128 v[158:161], v162 offset:2048
	ds_read_b128 v[162:165], v162 offset:3072
	ds_read_b128 v[166:169], v178
	ds_read_b128 v[170:173], v178 offset:1024
	ds_read_b128 v[174:177], v178 offset:2048
	ds_read_b128 v[178:181], v178 offset:3072
	s_add_u32 s24, s58, 0x80000
	s_addc_u32 s25, s59, 0
	s_mov_b32 m0, s61
	v_lshl_add_u64 v[224:225], s[24:25], 0, v[128:129]
	ds_read_b128 v[182:185], v153 offset:32768
	ds_read_b128 v[186:189], v153 offset:33792
	ds_read_b128 v[190:193], v153 offset:34816
	ds_read_b128 v[194:197], v153 offset:35840
	ds_read_b128 v[198:201], v153 offset:36864
	ds_read_b128 v[202:205], v153 offset:37888
	ds_read_b128 v[206:209], v153 offset:38912
	ds_read_b128 v[212:215], v153 offset:39936
	global_load_lds_dwordx4 v[224:225], off
	v_lshl_add_u64 v[224:225], s[24:25], 0, v[132:133]
	s_mov_b32 m0, s62
	s_nop 0
	global_load_lds_dwordx4 v[224:225], off
	s_waitcnt vmcnt(8)
	s_waitcnt lgkmcnt(0)
	s_barrier
	s_waitcnt lgkmcnt(0)
	v_mfma_f32_16x16x32_bf16 v[124:127], v[144:147], v[182:185], v[124:127]
	v_mfma_f32_16x16x32_bf16 v[120:123], v[158:161], v[182:185], v[120:123]
	v_mfma_f32_16x16x32_bf16 v[108:111], v[144:147], v[190:193], v[108:111]
	v_mfma_f32_16x16x32_bf16 v[104:107], v[158:161], v[190:193], v[104:107]
	v_mfma_f32_16x16x32_bf16 v[92:95], v[144:147], v[198:201], v[92:95]
	v_mfma_f32_16x16x32_bf16 v[88:91], v[158:161], v[198:201], v[88:91]
	v_mfma_f32_16x16x32_bf16 v[76:79], v[144:147], v[206:209], v[76:79]
	v_mfma_f32_16x16x32_bf16 v[72:75], v[158:161], v[206:209], v[72:75]
	v_mfma_f32_16x16x32_bf16 v[124:127], v[154:157], v[186:189], v[124:127]
	v_mfma_f32_16x16x32_bf16 v[120:123], v[162:165], v[186:189], v[120:123]
	v_mfma_f32_16x16x32_bf16 v[108:111], v[154:157], v[194:197], v[108:111]
	v_mfma_f32_16x16x32_bf16 v[104:107], v[162:165], v[194:197], v[104:107]
	v_mfma_f32_16x16x32_bf16 v[92:95], v[154:157], v[202:205], v[92:95]
	v_mfma_f32_16x16x32_bf16 v[88:91], v[162:165], v[202:205], v[88:91]
	v_mfma_f32_16x16x32_bf16 v[76:79], v[154:157], v[212:215], v[76:79]
	v_mfma_f32_16x16x32_bf16 v[72:75], v[162:165], v[212:215], v[72:75]
	v_mfma_f32_16x16x32_bf16 v[116:119], v[166:169], v[182:185], v[116:119]
	v_mfma_f32_16x16x32_bf16 v[112:115], v[174:177], v[182:185], v[112:115]
	v_mfma_f32_16x16x32_bf16 v[100:103], v[166:169], v[190:193], v[100:103]
	v_mfma_f32_16x16x32_bf16 v[96:99], v[174:177], v[190:193], v[96:99]
	v_mfma_f32_16x16x32_bf16 v[84:87], v[166:169], v[198:201], v[84:87]
	v_mfma_f32_16x16x32_bf16 v[80:83], v[174:177], v[198:201], v[80:83]
	v_mfma_f32_16x16x32_bf16 v[68:71], v[166:169], v[206:209], v[68:71]
	v_mfma_f32_16x16x32_bf16 v[64:67], v[174:177], v[206:209], v[64:67]
	v_mfma_f32_16x16x32_bf16 v[116:119], v[170:173], v[186:189], v[116:119]
	v_mfma_f32_16x16x32_bf16 v[112:115], v[178:181], v[186:189], v[112:115]
	v_mfma_f32_16x16x32_bf16 v[100:103], v[170:173], v[194:197], v[100:103]
	v_mfma_f32_16x16x32_bf16 v[96:99], v[178:181], v[194:197], v[96:99]
	v_mfma_f32_16x16x32_bf16 v[84:87], v[170:173], v[202:205], v[84:87]
	v_mfma_f32_16x16x32_bf16 v[80:83], v[178:181], v[202:205], v[80:83]
	v_mfma_f32_16x16x32_bf16 v[68:71], v[170:173], v[212:215], v[68:71]
	v_mfma_f32_16x16x32_bf16 v[64:67], v[178:181], v[212:215], v[64:67]
	s_barrier
	s_add_i32 s24, s26, s33
	v_lshl_add_u64 v[216:217], v[216:217], 0, s[20:21]
	s_mov_b32 m0, s24
	ds_read_b128 v[182:185], v153 offset:49152
	ds_read_b128 v[186:189], v153 offset:50176
	ds_read_b128 v[190:193], v153 offset:51200
	ds_read_b128 v[194:197], v153 offset:52224
	ds_read_b128 v[198:201], v153 offset:53248
	ds_read_b128 v[202:205], v153 offset:54272
	ds_read_b128 v[206:209], v153 offset:55296
	ds_read_b128 v[212:215], v153 offset:56320
	global_load_lds_dwordx4 v[216:217], off
	s_add_i32 m0, s24, 0x2000
	s_add_u32 s24, s56, 0x80080
	v_lshl_add_u64 v[216:217], v[218:219], 0, s[20:21]
	s_addc_u32 s25, s57, 0
	s_add_i32 s26, s27, s33
	global_load_lds_dwordx4 v[216:217], off
	v_lshl_add_u64 v[216:217], s[24:25], 0, v[130:131]
	s_mov_b32 m0, s26
	s_nop 0
	global_load_lds_dwordx4 v[216:217], off
	v_lshl_add_u64 v[216:217], s[24:25], 0, v[134:135]
	s_add_i32 m0, s26, 0x2000
	s_nop 0
	global_load_lds_dwordx4 v[216:217], off
	v_lshl_add_u64 v[216:217], v[220:221], 0, s[20:21]
	s_mov_b32 m0, s64
	s_nop 0
	global_load_lds_dwordx4 v[216:217], off
	v_lshl_add_u64 v[216:217], v[222:223], 0, s[20:21]
	s_mov_b32 m0, s65
	s_nop 0
	global_load_lds_dwordx4 v[216:217], off
	s_waitcnt vmcnt(8)
	s_waitcnt lgkmcnt(0)
	s_barrier
	s_waitcnt lgkmcnt(0)
	v_mfma_f32_16x16x32_bf16 v[60:63], v[144:147], v[182:185], v[60:63]
	v_mfma_f32_16x16x32_bf16 v[56:59], v[158:161], v[182:185], v[56:59]
	v_mfma_f32_16x16x32_bf16 v[44:47], v[144:147], v[190:193], v[44:47]
	v_mfma_f32_16x16x32_bf16 v[40:43], v[158:161], v[190:193], v[40:43]
	v_mfma_f32_16x16x32_bf16 v[28:31], v[144:147], v[198:201], v[28:31]
	v_mfma_f32_16x16x32_bf16 v[24:27], v[158:161], v[198:201], v[24:27]
	v_mfma_f32_16x16x32_bf16 v[12:15], v[144:147], v[206:209], v[12:15]
	v_mfma_f32_16x16x32_bf16 v[8:11], v[158:161], v[206:209], v[8:11]
	v_mfma_f32_16x16x32_bf16 v[60:63], v[154:157], v[186:189], v[60:63]
	v_mfma_f32_16x16x32_bf16 v[56:59], v[162:165], v[186:189], v[56:59]
	v_mfma_f32_16x16x32_bf16 v[44:47], v[154:157], v[194:197], v[44:47]
	v_mfma_f32_16x16x32_bf16 v[40:43], v[162:165], v[194:197], v[40:43]
	v_mfma_f32_16x16x32_bf16 v[28:31], v[154:157], v[202:205], v[28:31]
	v_mfma_f32_16x16x32_bf16 v[24:27], v[162:165], v[202:205], v[24:27]
	v_mfma_f32_16x16x32_bf16 v[12:15], v[154:157], v[212:215], v[12:15]
	v_mfma_f32_16x16x32_bf16 v[8:11], v[162:165], v[212:215], v[8:11]
	v_mfma_f32_16x16x32_bf16 v[52:55], v[166:169], v[182:185], v[52:55]
	v_mfma_f32_16x16x32_bf16 v[48:51], v[174:177], v[182:185], v[48:51]
	v_mfma_f32_16x16x32_bf16 v[36:39], v[166:169], v[190:193], v[36:39]
	v_mfma_f32_16x16x32_bf16 v[32:35], v[174:177], v[190:193], v[32:35]
	v_mfma_f32_16x16x32_bf16 v[20:23], v[166:169], v[198:201], v[20:23]
	v_mfma_f32_16x16x32_bf16 v[16:19], v[174:177], v[198:201], v[16:19]
	v_mfma_f32_16x16x32_bf16 v[4:7], v[166:169], v[206:209], v[4:7]
	v_mfma_f32_16x16x32_bf16 v[0:3], v[174:177], v[206:209], v[0:3]
	v_mfma_f32_16x16x32_bf16 v[52:55], v[170:173], v[186:189], v[52:55]
	v_mfma_f32_16x16x32_bf16 v[48:51], v[178:181], v[186:189], v[48:51]
	v_mfma_f32_16x16x32_bf16 v[36:39], v[170:173], v[194:197], v[36:39]
	v_mfma_f32_16x16x32_bf16 v[32:35], v[178:181], v[194:197], v[32:35]
	v_mfma_f32_16x16x32_bf16 v[20:23], v[170:173], v[202:205], v[20:23]
	v_mfma_f32_16x16x32_bf16 v[16:19], v[178:181], v[202:205], v[16:19]
	v_mfma_f32_16x16x32_bf16 v[4:7], v[170:173], v[212:215], v[4:7]
	v_mfma_f32_16x16x32_bf16 v[0:3], v[178:181], v[212:215], v[0:3]
	s_barrier
	s_add_i32 s77, s77, 2
	s_add_u32 s54, s54, 0x100
	s_addc_u32 s55, s55, 0
	s_add_u32 s69, s69, 0x100
	s_addc_u32 s76, s76, 0
	s_cmp_gt_u32 s77, 29
	s_cbranch_scc0 .LBB0_1239
	s_and_b64 vcc, exec, s[42:43]
	s_cbranch_vccz .LBB0_1242
	s_barrier

.LBB0_1314:
	s_or_b64 exec, exec, s[2:3]
	s_setprio 0
	s_waitcnt lgkmcnt(0)
	s_barrier
	v_readlane_b32 s3, v233, 20
	v_readfirstlane_b32 s2, v210
	s_ashr_i32 s2, s2, 6
	s_add_i32 s2, s2, s3
	v_readlane_b32 s16, v233, 39
	s_cmpk_gt_i32 s2, 0x3fff
	v_readlane_b32 s30, v233, 53
	v_readlane_b32 s31, v233, 54
	v_readlane_b32 s17, v233, 40
	v_readlane_b32 s18, v233, 41
	v_readlane_b32 s19, v233, 42
	v_readlane_b32 s20, v233, 43
	v_readlane_b32 s21, v233, 44
	v_readlane_b32 s22, v233, 45
	v_readlane_b32 s23, v233, 46
	v_readlane_b32 s24, v233, 47
	v_readlane_b32 s25, v233, 48
	v_readlane_b32 s26, v233, 49
	v_readlane_b32 s27, v233, 50
	v_readlane_b32 s28, v233, 51
	v_readlane_b32 s29, v233, 52
	s_cbranch_scc1 .LBB0_1321
	s_mov_b64 s[14:15], s[30:31]
	v_and_b32_e32 v38, 63, v210
	v_readlane_b32 s16, v233, 2
	v_lshlrev_b32_e32 v32, 4, v38
	v_mov_b32_e32 v33, 0
	v_readlane_b32 s22, v233, 8
	v_readlane_b32 s23, v233, 9
	s_mov_b64 s[4:5], 0x2000
	s_ashr_i32 s3, s2, 31
	v_lshl_add_u64 v[24:25], s[22:23], 0, v[32:33]
	v_lshl_add_u64 v[26:27], v[24:25], 0, s[4:5]
	s_lshl_b64 s[4:5], s[2:3], 12
	s_add_u32 s6, s6, s4
	s_addc_u32 s7, s7, s5
	v_add_co_u32_e32 v34, vcc, 0x3000, v24
	s_add_u32 s4, s12, s4
	s_nop 0
	v_addc_co_u32_e32 v35, vcc, 0, v25, vcc
	s_addc_u32 s5, s13, s5
	s_lshl_b64 s[8:9], s[2:3], 2
	v_add_co_u32_e32 v36, vcc, 0x2000, v24
	s_add_u32 s0, s0, s8
	s_nop 0
	v_addc_co_u32_e32 v37, vcc, 0, v25, vcc
	s_addc_u32 s1, s1, s9
	global_load_dwordx4 v[0:3], v[34:35], off offset:2048
	global_load_dwordx4 v[4:7], v[34:35], off offset:1024
	global_load_dwordx4 v[8:11], v[34:35], off
	global_load_dwordx4 v[12:15], v[26:27], off offset:3072
	global_load_dwordx4 v[16:19], v[26:27], off offset:2048
	global_load_dwordx4 v[20:23], v[26:27], off offset:1024
	s_nop 0
	global_load_dwordx4 v[24:27], v[34:35], off offset:3072
	global_load_dwordx4 v[28:31], v[36:37], off
	v_lshlrev_b32_e32 v68, 3, v38
	global_load_dword v102, v33, s[0:1]
	global_load_dwordx2 v[34:35], v68, s[6:7] nt
	global_load_dwordx2 v[36:37], v68, s[6:7] offset:512 nt
	global_load_dwordx2 v[38:39], v68, s[6:7] offset:1024 nt
	global_load_dwordx2 v[40:41], v68, s[6:7] offset:1536 nt
	global_load_dwordx2 v[56:57], v68, s[4:5] nt
	global_load_dwordx2 v[54:55], v68, s[4:5] offset:512 nt
	global_load_dwordx2 v[52:53], v68, s[4:5] offset:1024 nt
	global_load_dwordx2 v[50:51], v68, s[4:5] offset:1536 nt
	global_load_dwordx2 v[42:43], v68, s[6:7] offset:2048 nt
	global_load_dwordx2 v[44:45], v68, s[6:7] offset:2560 nt
	global_load_dwordx2 v[46:47], v68, s[6:7] offset:3072 nt
	global_load_dwordx2 v[48:49], v68, s[6:7] offset:3584 nt
	global_load_dwordx2 v[60:61], v68, s[4:5] offset:2048 nt
	global_load_dwordx2 v[58:59], v68, s[4:5] offset:2560 nt
	global_load_dwordx2 v[64:65], v68, s[4:5] offset:3072 nt
	global_load_dwordx2 v[62:63], v68, s[4:5] offset:3584 nt
	s_lshl_b64 s[0:1], s[2:3], 13
	s_add_u32 s0, s14, s0
	s_addc_u32 s1, s15, s1
	v_lshl_add_u64 v[66:67], s[0:1], 0, v[32:33]
	s_mov_b64 s[0:1], 0x1000
	v_lshl_add_u64 v[66:67], v[66:67], 0, s[0:1]
	s_add_i32 s0, s2, s96
	s_ashr_i32 s1, s0, 31
	s_ashr_i32 s97, s96, 31
	s_lshl_b64 s[6:7], s[0:1], 12
	s_lshl_b64 s[4:5], s[96:97], 13
	v_or_b32_e32 v68, s6, v68
	v_mov_b32_e32 v69, s7
	s_lshl_b64 s[6:7], s[96:97], 12
	s_lshl_b64 s[0:1], s[0:1], 2
	s_add_u32 s3, s0, 0x30000
	s_addc_u32 s14, s1, 0
	s_lshl_b64 s[8:9], s[96:97], 2
	v_mov_b32_e32 v32, 0x358637bd
	s_mov_b32 s15, 0xf800000
	v_mov_b32_e32 v103, 0x260
	v_readlane_b32 s17, v233, 3
	v_readlane_b32 s18, v233, 4
	v_readlane_b32 s19, v233, 5
	v_readlane_b32 s20, v233, 6
	v_readlane_b32 s21, v233, 7
	v_readlane_b32 s24, v233, 10
	v_readlane_b32 s25, v233, 11
	v_readlane_b32 s26, v233, 12
	v_readlane_b32 s27, v233, 13
	v_readlane_b32 s28, v233, 14
	v_readlane_b32 s29, v233, 15
	v_readlane_b32 s30, v233, 16
	v_readlane_b32 s31, v233, 17
	s_waitcnt vmcnt(0)
	s_branch .LBB0_1317
